# GEMM K-loops: counter updates and exit test moved above the loop-back barrier (back-edge rotation)
# baseline (speedup 1.0000x reference)
.LBB0_218:
	ds_read_b128 v[152:155], v149
	ds_read_b128 v[156:159], v149 offset:1024
	ds_read_b128 v[160:163], v149 offset:2048
	ds_read_b128 v[164:167], v149 offset:3072
	ds_read_b128 v[168:171], v150
	ds_read_b128 v[172:175], v150 offset:1024
	ds_read_b128 v[176:179], v150 offset:2048
	ds_read_b128 v[180:183], v150 offset:3072
	s_add_u32 s45, s42, 0xfffc0080
	s_addc_u32 s48, s43, -1
	s_cmp_eq_u32 s44, 12
	s_cselect_b32 s57, s39, s48
	s_cselect_b32 s56, s38, s45
	s_cselect_b32 s49, s41, s31
	s_cselect_b32 s48, s40, s27
	v_lshl_add_u64 v[216:217], s[42:43], 0, v[138:139]
	s_add_i32 m0, s29, 0xc000
	ds_read_b128 v[184:187], v151
	ds_read_b128 v[188:191], v151 offset:1024
	ds_read_b128 v[192:195], v151 offset:2048
	ds_read_b128 v[196:199], v151 offset:3072
	ds_read_b128 v[200:203], v151 offset:4096
	ds_read_b128 v[204:207], v151 offset:5120
	ds_read_b128 v[208:211], v151 offset:6144
	ds_read_b128 v[212:215], v151 offset:7168
	global_load_lds_dwordx4 v[216:217], off
	v_lshl_add_u64 v[216:217], s[42:43], 0, v[140:141]
	s_add_i32 m0, s29, 0xe000
	s_nop 0
	global_load_lds_dwordx4 v[216:217], off
	s_waitcnt vmcnt(8)
	s_waitcnt lgkmcnt(0)
	s_barrier
	s_waitcnt lgkmcnt(0)
	v_mfma_f32_16x16x32_bf16 v[126:129], v[152:155], v[184:187], v[126:129]
	v_mfma_f32_16x16x32_bf16 v[122:125], v[160:163], v[184:187], v[122:125]
	v_mfma_f32_16x16x32_bf16 v[118:121], v[152:155], v[192:195], v[118:121]
	v_mfma_f32_16x16x32_bf16 v[114:117], v[160:163], v[192:195], v[114:117]
	v_mfma_f32_16x16x32_bf16 v[102:105], v[152:155], v[200:203], v[102:105]
	v_mfma_f32_16x16x32_bf16 v[98:101], v[160:163], v[200:203], v[98:101]
	v_mfma_f32_16x16x32_bf16 v[86:89], v[152:155], v[208:211], v[86:89]
	v_mfma_f32_16x16x32_bf16 v[82:85], v[160:163], v[208:211], v[82:85]
	v_mfma_f32_16x16x32_bf16 v[126:129], v[156:159], v[188:191], v[126:129]
	v_mfma_f32_16x16x32_bf16 v[122:125], v[164:167], v[188:191], v[122:125]
	v_mfma_f32_16x16x32_bf16 v[118:121], v[156:159], v[196:199], v[118:121]
	v_mfma_f32_16x16x32_bf16 v[114:117], v[164:167], v[196:199], v[114:117]
	v_mfma_f32_16x16x32_bf16 v[102:105], v[156:159], v[204:207], v[102:105]
	v_mfma_f32_16x16x32_bf16 v[98:101], v[164:167], v[204:207], v[98:101]
	v_mfma_f32_16x16x32_bf16 v[86:89], v[156:159], v[212:215], v[86:89]
	v_mfma_f32_16x16x32_bf16 v[82:85], v[164:167], v[212:215], v[82:85]
	v_mfma_f32_16x16x32_bf16 v[110:113], v[168:171], v[184:187], v[110:113]
	v_mfma_f32_16x16x32_bf16 v[106:109], v[176:179], v[184:187], v[106:109]
	v_mfma_f32_16x16x32_bf16 v[94:97], v[168:171], v[192:195], v[94:97]
	v_mfma_f32_16x16x32_bf16 v[90:93], v[176:179], v[192:195], v[90:93]
	v_mfma_f32_16x16x32_bf16 v[78:81], v[168:171], v[200:203], v[78:81]
	v_mfma_f32_16x16x32_bf16 v[74:77], v[176:179], v[200:203], v[74:77]
	v_mfma_f32_16x16x32_bf16 v[70:73], v[168:171], v[208:211], v[70:73]
	v_mfma_f32_16x16x32_bf16 v[66:69], v[176:179], v[208:211], v[66:69]
	v_mfma_f32_16x16x32_bf16 v[110:113], v[172:175], v[188:191], v[110:113]
	v_mfma_f32_16x16x32_bf16 v[106:109], v[180:183], v[188:191], v[106:109]
	v_mfma_f32_16x16x32_bf16 v[94:97], v[172:175], v[196:199], v[94:97]
	v_mfma_f32_16x16x32_bf16 v[90:93], v[180:183], v[196:199], v[90:93]
	v_mfma_f32_16x16x32_bf16 v[78:81], v[172:175], v[204:207], v[78:81]
	v_mfma_f32_16x16x32_bf16 v[74:77], v[180:183], v[204:207], v[74:77]
	v_mfma_f32_16x16x32_bf16 v[70:73], v[172:175], v[212:215], v[70:73]
	v_mfma_f32_16x16x32_bf16 v[66:69], v[180:183], v[212:215], v[66:69]
	s_barrier
	s_add_i32 s45, s80, s59
	v_lshl_add_u64 v[216:217], s[48:49], 0, v[132:133]
	s_mov_b32 m0, s45
	ds_read_b128 v[184:187], v151 offset:16384
	ds_read_b128 v[188:191], v151 offset:17408
	ds_read_b128 v[192:195], v151 offset:18432
	ds_read_b128 v[196:199], v151 offset:19456
	ds_read_b128 v[200:203], v151 offset:20480
	ds_read_b128 v[204:207], v151 offset:21504
	ds_read_b128 v[208:211], v151 offset:22528
	ds_read_b128 v[212:215], v151 offset:23552
	global_load_lds_dwordx4 v[216:217], off
	s_add_i32 m0, s45, 0x2000
	s_add_u32 s92, s48, 0x40000
	v_lshl_add_u64 v[218:219], s[48:49], 0, v[136:137]
	s_addc_u32 s93, s49, 0
	s_add_i32 s45, s81, s59
	global_load_lds_dwordx4 v[218:219], off
	v_lshl_add_u64 v[220:221], s[92:93], 0, v[132:133]
	s_mov_b32 m0, s45
	v_lshl_add_u64 v[222:223], s[56:57], 0, v[134:135]
	global_load_lds_dwordx4 v[220:221], off
	v_lshl_add_u64 v[220:221], s[92:93], 0, v[136:137]
	s_add_i32 m0, s45, 0x2000
	s_nop 0
	global_load_lds_dwordx4 v[220:221], off
	v_lshl_add_u64 v[220:221], s[56:57], 0, v[130:131]
	s_mov_b32 m0, s29
	s_nop 0
	global_load_lds_dwordx4 v[220:221], off
	s_mov_b32 m0, s62
	s_nop 0
	global_load_lds_dwordx4 v[222:223], off
	s_waitcnt vmcnt(8)
	s_waitcnt lgkmcnt(0)
	s_barrier
	s_waitcnt lgkmcnt(0)
	v_mfma_f32_16x16x32_bf16 v[62:65], v[152:155], v[184:187], v[62:65]
	v_mfma_f32_16x16x32_bf16 v[58:61], v[160:163], v[184:187], v[58:61]
	v_mfma_f32_16x16x32_bf16 v[54:57], v[152:155], v[192:195], v[54:57]
	v_mfma_f32_16x16x32_bf16 v[50:53], v[160:163], v[192:195], v[50:53]
	v_mfma_f32_16x16x32_bf16 v[38:41], v[152:155], v[200:203], v[38:41]
	v_mfma_f32_16x16x32_bf16 v[34:37], v[160:163], v[200:203], v[34:37]
	v_mfma_f32_16x16x32_bf16 v[22:25], v[152:155], v[208:211], v[22:25]
	v_mfma_f32_16x16x32_bf16 v[18:21], v[160:163], v[208:211], v[18:21]
	v_mfma_f32_16x16x32_bf16 v[62:65], v[156:159], v[188:191], v[62:65]
	v_mfma_f32_16x16x32_bf16 v[58:61], v[164:167], v[188:191], v[58:61]
	v_mfma_f32_16x16x32_bf16 v[54:57], v[156:159], v[196:199], v[54:57]
	v_mfma_f32_16x16x32_bf16 v[50:53], v[164:167], v[196:199], v[50:53]
	v_mfma_f32_16x16x32_bf16 v[38:41], v[156:159], v[204:207], v[38:41]
	v_mfma_f32_16x16x32_bf16 v[34:37], v[164:167], v[204:207], v[34:37]
	v_mfma_f32_16x16x32_bf16 v[22:25], v[156:159], v[212:215], v[22:25]
	v_mfma_f32_16x16x32_bf16 v[18:21], v[164:167], v[212:215], v[18:21]
	v_mfma_f32_16x16x32_bf16 v[46:49], v[168:171], v[184:187], v[46:49]
	v_mfma_f32_16x16x32_bf16 v[42:45], v[176:179], v[184:187], v[42:45]
	v_mfma_f32_16x16x32_bf16 v[30:33], v[168:171], v[192:195], v[30:33]
	v_mfma_f32_16x16x32_bf16 v[26:29], v[176:179], v[192:195], v[26:29]
	v_mfma_f32_16x16x32_bf16 v[14:17], v[168:171], v[200:203], v[14:17]
	v_mfma_f32_16x16x32_bf16 v[10:13], v[176:179], v[200:203], v[10:13]
	v_mfma_f32_16x16x32_bf16 v[6:9], v[168:171], v[208:211], v[6:9]
	v_mfma_f32_16x16x32_bf16 v[2:5], v[176:179], v[208:211], v[2:5]
	v_mfma_f32_16x16x32_bf16 v[46:49], v[172:175], v[188:191], v[46:49]
	v_mfma_f32_16x16x32_bf16 v[42:45], v[180:183], v[188:191], v[42:45]
	v_mfma_f32_16x16x32_bf16 v[30:33], v[172:175], v[196:199], v[30:33]
	v_mfma_f32_16x16x32_bf16 v[26:29], v[180:183], v[196:199], v[26:29]
	v_mfma_f32_16x16x32_bf16 v[14:17], v[172:175], v[204:207], v[14:17]
	v_mfma_f32_16x16x32_bf16 v[10:13], v[180:183], v[204:207], v[10:13]
	v_mfma_f32_16x16x32_bf16 v[6:9], v[172:175], v[212:215], v[6:9]
	v_mfma_f32_16x16x32_bf16 v[2:5], v[180:183], v[212:215], v[2:5]
	s_barrier
	s_add_i32 s45, 0, 0x18000
	s_add_i32 s91, 0, 0x1c000
	v_add_u32_e32 v164, s45, v147
	v_add_u32_e32 v180, s91, v147
	ds_read_b128 v[152:155], v164
	ds_read_b128 v[156:159], v164 offset:1024
	ds_read_b128 v[160:163], v164 offset:2048
	ds_read_b128 v[164:167], v164 offset:3072
	ds_read_b128 v[168:171], v180
	ds_read_b128 v[172:175], v180 offset:1024
	ds_read_b128 v[176:179], v180 offset:2048
	ds_read_b128 v[180:183], v180 offset:3072
	s_add_u32 s56, s56, 0x40000
	s_addc_u32 s57, s57, 0
	s_mov_b32 m0, s63
	v_lshl_add_u64 v[224:225], s[56:57], 0, v[130:131]
	ds_read_b128 v[184:187], v151 offset:32768
	ds_read_b128 v[188:191], v151 offset:33792
	ds_read_b128 v[192:195], v151 offset:34816
	ds_read_b128 v[196:199], v151 offset:35840
	ds_read_b128 v[200:203], v151 offset:36864
	ds_read_b128 v[204:207], v151 offset:37888
	ds_read_b128 v[208:211], v151 offset:38912
	ds_read_b128 v[212:215], v151 offset:39936
	global_load_lds_dwordx4 v[224:225], off
	v_lshl_add_u64 v[224:225], s[56:57], 0, v[134:135]
	s_mov_b32 m0, s74
	s_nop 0
	global_load_lds_dwordx4 v[224:225], off
	s_waitcnt vmcnt(8)
	s_waitcnt lgkmcnt(0)
	s_barrier
	s_waitcnt lgkmcnt(0)
	v_mfma_f32_16x16x32_bf16 v[126:129], v[152:155], v[184:187], v[126:129]
	v_mfma_f32_16x16x32_bf16 v[122:125], v[160:163], v[184:187], v[122:125]
	v_mfma_f32_16x16x32_bf16 v[118:121], v[152:155], v[192:195], v[118:121]
	v_mfma_f32_16x16x32_bf16 v[114:117], v[160:163], v[192:195], v[114:117]
	v_mfma_f32_16x16x32_bf16 v[102:105], v[152:155], v[200:203], v[102:105]
	v_mfma_f32_16x16x32_bf16 v[98:101], v[160:163], v[200:203], v[98:101]
	v_mfma_f32_16x16x32_bf16 v[86:89], v[152:155], v[208:211], v[86:89]
	v_mfma_f32_16x16x32_bf16 v[82:85], v[160:163], v[208:211], v[82:85]
	v_mfma_f32_16x16x32_bf16 v[126:129], v[156:159], v[188:191], v[126:129]
	v_mfma_f32_16x16x32_bf16 v[122:125], v[164:167], v[188:191], v[122:125]
	v_mfma_f32_16x16x32_bf16 v[118:121], v[156:159], v[196:199], v[118:121]
	v_mfma_f32_16x16x32_bf16 v[114:117], v[164:167], v[196:199], v[114:117]
	v_mfma_f32_16x16x32_bf16 v[102:105], v[156:159], v[204:207], v[102:105]
	v_mfma_f32_16x16x32_bf16 v[98:101], v[164:167], v[204:207], v[98:101]
	v_mfma_f32_16x16x32_bf16 v[86:89], v[156:159], v[212:215], v[86:89]
	v_mfma_f32_16x16x32_bf16 v[82:85], v[164:167], v[212:215], v[82:85]
	v_mfma_f32_16x16x32_bf16 v[110:113], v[168:171], v[184:187], v[110:113]
	v_mfma_f32_16x16x32_bf16 v[106:109], v[176:179], v[184:187], v[106:109]
	v_mfma_f32_16x16x32_bf16 v[94:97], v[168:171], v[192:195], v[94:97]
	v_mfma_f32_16x16x32_bf16 v[90:93], v[176:179], v[192:195], v[90:93]
	v_mfma_f32_16x16x32_bf16 v[78:81], v[168:171], v[200:203], v[78:81]
	v_mfma_f32_16x16x32_bf16 v[74:77], v[176:179], v[200:203], v[74:77]
	v_mfma_f32_16x16x32_bf16 v[70:73], v[168:171], v[208:211], v[70:73]
	v_mfma_f32_16x16x32_bf16 v[66:69], v[176:179], v[208:211], v[66:69]
	v_mfma_f32_16x16x32_bf16 v[110:113], v[172:175], v[188:191], v[110:113]
	v_mfma_f32_16x16x32_bf16 v[106:109], v[180:183], v[188:191], v[106:109]
	v_mfma_f32_16x16x32_bf16 v[94:97], v[172:175], v[196:199], v[94:97]
	v_mfma_f32_16x16x32_bf16 v[90:93], v[180:183], v[196:199], v[90:93]
	v_mfma_f32_16x16x32_bf16 v[78:81], v[172:175], v[204:207], v[78:81]
	v_mfma_f32_16x16x32_bf16 v[74:77], v[180:183], v[204:207], v[74:77]
	v_mfma_f32_16x16x32_bf16 v[70:73], v[172:175], v[212:215], v[70:73]
	v_mfma_f32_16x16x32_bf16 v[66:69], v[180:183], v[212:215], v[66:69]
	s_barrier
	s_add_i32 s45, s45, s59
	v_lshl_add_u64 v[216:217], v[216:217], 0, s[14:15]
	s_mov_b32 m0, s45
	ds_read_b128 v[184:187], v151 offset:49152
	ds_read_b128 v[188:191], v151 offset:50176
	ds_read_b128 v[192:195], v151 offset:51200
	ds_read_b128 v[196:199], v151 offset:52224
	ds_read_b128 v[200:203], v151 offset:53248
	ds_read_b128 v[204:207], v151 offset:54272
	ds_read_b128 v[208:211], v151 offset:55296
	ds_read_b128 v[212:215], v151 offset:56320
	global_load_lds_dwordx4 v[216:217], off
	s_add_i32 m0, s45, 0x2000
	s_add_u32 s48, s48, 0x40080
	v_lshl_add_u64 v[216:217], v[218:219], 0, s[14:15]
	s_addc_u32 s49, s49, 0
	s_add_i32 s45, s91, s59
	global_load_lds_dwordx4 v[216:217], off
	v_lshl_add_u64 v[216:217], s[48:49], 0, v[132:133]
	s_mov_b32 m0, s45
	s_nop 0
	global_load_lds_dwordx4 v[216:217], off
	v_lshl_add_u64 v[216:217], s[48:49], 0, v[136:137]
	s_add_i32 m0, s45, 0x2000
	s_nop 0
	global_load_lds_dwordx4 v[216:217], off
	v_lshl_add_u64 v[216:217], v[220:221], 0, s[14:15]
	s_mov_b32 m0, s77
	s_nop 0
	global_load_lds_dwordx4 v[216:217], off
	v_lshl_add_u64 v[216:217], v[222:223], 0, s[14:15]
	s_mov_b32 m0, s78
	s_nop 0
	global_load_lds_dwordx4 v[216:217], off
	s_waitcnt vmcnt(8)
	s_waitcnt lgkmcnt(0)
	s_barrier
	s_waitcnt lgkmcnt(0)
	v_mfma_f32_16x16x32_bf16 v[62:65], v[152:155], v[184:187], v[62:65]
	v_mfma_f32_16x16x32_bf16 v[58:61], v[160:163], v[184:187], v[58:61]
	v_mfma_f32_16x16x32_bf16 v[54:57], v[152:155], v[192:195], v[54:57]
	v_mfma_f32_16x16x32_bf16 v[50:53], v[160:163], v[192:195], v[50:53]
	v_mfma_f32_16x16x32_bf16 v[38:41], v[152:155], v[200:203], v[38:41]
	v_mfma_f32_16x16x32_bf16 v[34:37], v[160:163], v[200:203], v[34:37]
	v_mfma_f32_16x16x32_bf16 v[22:25], v[152:155], v[208:211], v[22:25]
	v_mfma_f32_16x16x32_bf16 v[18:21], v[160:163], v[208:211], v[18:21]
	v_mfma_f32_16x16x32_bf16 v[62:65], v[156:159], v[188:191], v[62:65]
	v_mfma_f32_16x16x32_bf16 v[58:61], v[164:167], v[188:191], v[58:61]
	v_mfma_f32_16x16x32_bf16 v[54:57], v[156:159], v[196:199], v[54:57]
	v_mfma_f32_16x16x32_bf16 v[50:53], v[164:167], v[196:199], v[50:53]
	v_mfma_f32_16x16x32_bf16 v[38:41], v[156:159], v[204:207], v[38:41]
	v_mfma_f32_16x16x32_bf16 v[34:37], v[164:167], v[204:207], v[34:37]
	v_mfma_f32_16x16x32_bf16 v[22:25], v[156:159], v[212:215], v[22:25]
	v_mfma_f32_16x16x32_bf16 v[18:21], v[164:167], v[212:215], v[18:21]
	v_mfma_f32_16x16x32_bf16 v[46:49], v[168:171], v[184:187], v[46:49]
	v_mfma_f32_16x16x32_bf16 v[42:45], v[176:179], v[184:187], v[42:45]
	v_mfma_f32_16x16x32_bf16 v[30:33], v[168:171], v[192:195], v[30:33]
	v_mfma_f32_16x16x32_bf16 v[26:29], v[176:179], v[192:195], v[26:29]
	v_mfma_f32_16x16x32_bf16 v[14:17], v[168:171], v[200:203], v[14:17]
	v_mfma_f32_16x16x32_bf16 v[10:13], v[176:179], v[200:203], v[10:13]
	v_mfma_f32_16x16x32_bf16 v[6:9], v[168:171], v[208:211], v[6:9]
	v_mfma_f32_16x16x32_bf16 v[2:5], v[176:179], v[208:211], v[2:5]
	v_mfma_f32_16x16x32_bf16 v[46:49], v[172:175], v[188:191], v[46:49]
	v_mfma_f32_16x16x32_bf16 v[42:45], v[180:183], v[188:191], v[42:45]
	v_mfma_f32_16x16x32_bf16 v[30:33], v[172:175], v[196:199], v[30:33]
	v_mfma_f32_16x16x32_bf16 v[26:29], v[180:183], v[196:199], v[26:29]
	v_mfma_f32_16x16x32_bf16 v[14:17], v[172:175], v[204:207], v[14:17]
	v_mfma_f32_16x16x32_bf16 v[10:13], v[180:183], v[204:207], v[10:13]
	v_mfma_f32_16x16x32_bf16 v[6:9], v[172:175], v[212:215], v[6:9]
	v_mfma_f32_16x16x32_bf16 v[2:5], v[180:183], v[212:215], v[2:5]
	s_add_i32 s44, s44, 2
	s_add_u32 s42, s42, 0x100
	s_addc_u32 s43, s43, 0
	s_add_u32 s27, s27, 0x100
	s_addc_u32 s31, s31, 0
	s_cmp_gt_u32 s44, 13
	s_barrier
	s_cbranch_scc0 .LBB0_218
	s_and_b64 vcc, exec, s[16:17]
	s_cbranch_vccz .LBB0_221
	s_barrier

.LBB0_590:
	ds_read_b128 v[130:133], v175
	ds_read_b128 v[134:137], v175 offset:1024
	ds_read_b128 v[156:159], v175 offset:2048
	ds_read_b128 v[160:163], v175 offset:3072
	ds_read_b128 v[164:167], v176
	ds_read_b128 v[168:171], v176 offset:1024
	ds_read_b128 v[180:183], v176 offset:2048
	ds_read_b128 v[184:187], v176 offset:3072
	s_add_u32 s12, s10, 0xfffc0080
	s_addc_u32 s13, s11, -1
	s_cmp_eq_u32 s45, 12
	s_cselect_b32 s63, s7, s13
	s_cselect_b32 s62, s6, s12
	s_cselect_b32 s13, s9, s44
	s_cselect_b32 s12, s8, s16
	v_lshl_add_u64 v[220:221], s[10:11], 0, v[148:149]
	s_add_i32 m0, s78, 0xc000
	ds_read_b128 v[188:191], v177
	ds_read_b128 v[192:195], v177 offset:1024
	ds_read_b128 v[196:199], v177 offset:2048
	ds_read_b128 v[200:203], v177 offset:3072
	ds_read_b128 v[204:207], v177 offset:4096
	ds_read_b128 v[208:211], v177 offset:5120
	ds_read_b128 v[212:215], v177 offset:6144
	ds_read_b128 v[216:219], v177 offset:7168
	global_load_lds_dwordx4 v[220:221], off
	v_lshl_add_u64 v[220:221], s[10:11], 0, v[150:151]
	s_add_i32 m0, s78, 0xe000
	s_nop 0
	global_load_lds_dwordx4 v[220:221], off
	s_waitcnt vmcnt(8)
	s_waitcnt lgkmcnt(0)
	s_barrier
	s_waitcnt lgkmcnt(0)
	v_mfma_f32_16x16x32_bf16 v[126:129], v[130:133], v[188:191], v[126:129]
	v_mfma_f32_16x16x32_bf16 v[122:125], v[156:159], v[188:191], v[122:125]
	v_mfma_f32_16x16x32_bf16 v[118:121], v[130:133], v[196:199], v[118:121]
	v_mfma_f32_16x16x32_bf16 v[114:117], v[156:159], v[196:199], v[114:117]
	v_mfma_f32_16x16x32_bf16 v[110:113], v[130:133], v[204:207], v[110:113]
	v_mfma_f32_16x16x32_bf16 v[106:109], v[156:159], v[204:207], v[106:109]
	v_mfma_f32_16x16x32_bf16 v[102:105], v[130:133], v[212:215], v[102:105]
	v_mfma_f32_16x16x32_bf16 v[98:101], v[156:159], v[212:215], v[98:101]
	v_mfma_f32_16x16x32_bf16 v[126:129], v[134:137], v[192:195], v[126:129]
	v_mfma_f32_16x16x32_bf16 v[122:125], v[160:163], v[192:195], v[122:125]
	v_mfma_f32_16x16x32_bf16 v[118:121], v[134:137], v[200:203], v[118:121]
	v_mfma_f32_16x16x32_bf16 v[114:117], v[160:163], v[200:203], v[114:117]
	v_mfma_f32_16x16x32_bf16 v[110:113], v[134:137], v[208:211], v[110:113]
	v_mfma_f32_16x16x32_bf16 v[106:109], v[160:163], v[208:211], v[106:109]
	v_mfma_f32_16x16x32_bf16 v[102:105], v[134:137], v[216:219], v[102:105]
	v_mfma_f32_16x16x32_bf16 v[98:101], v[160:163], v[216:219], v[98:101]
	v_mfma_f32_16x16x32_bf16 v[62:65], v[164:167], v[188:191], v[62:65]
	v_mfma_f32_16x16x32_bf16 v[58:61], v[180:183], v[188:191], v[58:61]
	v_mfma_f32_16x16x32_bf16 v[54:57], v[164:167], v[196:199], v[54:57]
	v_mfma_f32_16x16x32_bf16 v[50:53], v[180:183], v[196:199], v[50:53]
	v_mfma_f32_16x16x32_bf16 v[46:49], v[164:167], v[204:207], v[46:49]
	v_mfma_f32_16x16x32_bf16 v[42:45], v[180:183], v[204:207], v[42:45]
	v_mfma_f32_16x16x32_bf16 v[38:41], v[164:167], v[212:215], v[38:41]
	v_mfma_f32_16x16x32_bf16 v[34:37], v[180:183], v[212:215], v[34:37]
	v_mfma_f32_16x16x32_bf16 v[62:65], v[168:171], v[192:195], v[62:65]
	v_mfma_f32_16x16x32_bf16 v[58:61], v[184:187], v[192:195], v[58:61]
	v_mfma_f32_16x16x32_bf16 v[54:57], v[168:171], v[200:203], v[54:57]
	v_mfma_f32_16x16x32_bf16 v[50:53], v[184:187], v[200:203], v[50:53]
	v_mfma_f32_16x16x32_bf16 v[46:49], v[168:171], v[208:211], v[46:49]
	v_mfma_f32_16x16x32_bf16 v[42:45], v[184:187], v[208:211], v[42:45]
	v_mfma_f32_16x16x32_bf16 v[38:41], v[168:171], v[216:219], v[38:41]
	v_mfma_f32_16x16x32_bf16 v[34:37], v[184:187], v[216:219], v[34:37]
	s_barrier
	s_add_i32 s46, s87, s61
	v_lshl_add_u64 v[220:221], s[12:13], 0, v[140:141]
	s_mov_b32 m0, s46
	ds_read_b128 v[188:191], v177 offset:16384
	ds_read_b128 v[192:195], v177 offset:17408
	ds_read_b128 v[196:199], v177 offset:18432
	ds_read_b128 v[200:203], v177 offset:19456
	ds_read_b128 v[204:207], v177 offset:20480
	ds_read_b128 v[208:211], v177 offset:21504
	ds_read_b128 v[212:215], v177 offset:22528
	ds_read_b128 v[216:219], v177 offset:23552
	global_load_lds_dwordx4 v[220:221], off
	s_add_i32 m0, s46, 0x2000
	s_add_u32 s46, s12, 0x40000
	v_lshl_add_u64 v[222:223], s[12:13], 0, v[144:145]
	s_addc_u32 s47, s13, 0
	s_add_i32 s55, s88, s61
	global_load_lds_dwordx4 v[222:223], off
	v_lshl_add_u64 v[224:225], s[46:47], 0, v[140:141]
	s_mov_b32 m0, s55
	v_lshl_add_u64 v[226:227], s[62:63], 0, v[142:143]
	global_load_lds_dwordx4 v[224:225], off
	v_lshl_add_u64 v[224:225], s[46:47], 0, v[144:145]
	s_add_i32 m0, s55, 0x2000
	s_nop 0
	global_load_lds_dwordx4 v[224:225], off
	v_lshl_add_u64 v[224:225], s[62:63], 0, v[138:139]
	s_mov_b32 m0, s78
	s_nop 0
	global_load_lds_dwordx4 v[224:225], off
	s_mov_b32 m0, s79
	s_nop 0
	global_load_lds_dwordx4 v[226:227], off
	s_waitcnt vmcnt(8)
	s_waitcnt lgkmcnt(0)
	s_barrier
	s_waitcnt lgkmcnt(0)
	v_mfma_f32_16x16x32_bf16 v[94:97], v[130:133], v[188:191], v[94:97]
	v_mfma_f32_16x16x32_bf16 v[90:93], v[156:159], v[188:191], v[90:93]
	v_mfma_f32_16x16x32_bf16 v[86:89], v[130:133], v[196:199], v[86:89]
	v_mfma_f32_16x16x32_bf16 v[82:85], v[156:159], v[196:199], v[82:85]
	v_mfma_f32_16x16x32_bf16 v[78:81], v[130:133], v[204:207], v[78:81]
	v_mfma_f32_16x16x32_bf16 v[74:77], v[156:159], v[204:207], v[74:77]
	v_mfma_f32_16x16x32_bf16 v[70:73], v[130:133], v[212:215], v[70:73]
	v_mfma_f32_16x16x32_bf16 v[66:69], v[156:159], v[212:215], v[66:69]
	v_mfma_f32_16x16x32_bf16 v[94:97], v[134:137], v[192:195], v[94:97]
	v_mfma_f32_16x16x32_bf16 v[90:93], v[160:163], v[192:195], v[90:93]
	v_mfma_f32_16x16x32_bf16 v[86:89], v[134:137], v[200:203], v[86:89]
	v_mfma_f32_16x16x32_bf16 v[82:85], v[160:163], v[200:203], v[82:85]
	v_mfma_f32_16x16x32_bf16 v[78:81], v[134:137], v[208:211], v[78:81]
	v_mfma_f32_16x16x32_bf16 v[74:77], v[160:163], v[208:211], v[74:77]
	v_mfma_f32_16x16x32_bf16 v[70:73], v[134:137], v[216:219], v[70:73]
	v_mfma_f32_16x16x32_bf16 v[66:69], v[160:163], v[216:219], v[66:69]
	v_mfma_f32_16x16x32_bf16 v[30:33], v[164:167], v[188:191], v[30:33]
	v_mfma_f32_16x16x32_bf16 v[26:29], v[180:183], v[188:191], v[26:29]
	v_mfma_f32_16x16x32_bf16 v[22:25], v[164:167], v[196:199], v[22:25]
	v_mfma_f32_16x16x32_bf16 v[18:21], v[180:183], v[196:199], v[18:21]
	v_mfma_f32_16x16x32_bf16 v[14:17], v[164:167], v[204:207], v[14:17]
	v_mfma_f32_16x16x32_bf16 v[10:13], v[180:183], v[204:207], v[10:13]
	v_mfma_f32_16x16x32_bf16 v[6:9], v[164:167], v[212:215], v[6:9]
	v_mfma_f32_16x16x32_bf16 v[2:5], v[180:183], v[212:215], v[2:5]
	v_mfma_f32_16x16x32_bf16 v[30:33], v[168:171], v[192:195], v[30:33]
	v_mfma_f32_16x16x32_bf16 v[26:29], v[184:187], v[192:195], v[26:29]
	v_mfma_f32_16x16x32_bf16 v[22:25], v[168:171], v[200:203], v[22:25]
	v_mfma_f32_16x16x32_bf16 v[18:21], v[184:187], v[200:203], v[18:21]
	v_mfma_f32_16x16x32_bf16 v[14:17], v[168:171], v[208:211], v[14:17]
	v_mfma_f32_16x16x32_bf16 v[10:13], v[184:187], v[208:211], v[10:13]
	v_mfma_f32_16x16x32_bf16 v[6:9], v[168:171], v[216:219], v[6:9]
	v_mfma_f32_16x16x32_bf16 v[2:5], v[184:187], v[216:219], v[2:5]
	s_barrier
	s_add_i32 s55, 0, 0x18000
	v_add_u32_e32 v146, s55, v173
	s_add_i32 s74, 0, 0x1c000
	ds_read_b128 v[130:133], v146
	ds_read_b128 v[134:137], v146 offset:1024
	ds_read_b128 v[156:159], v146 offset:2048
	ds_read_b128 v[160:163], v146 offset:3072
	v_add_u32_e32 v146, s74, v173
	ds_read_b128 v[164:167], v146
	ds_read_b128 v[168:171], v146 offset:1024
	ds_read_b128 v[180:183], v146 offset:2048
	ds_read_b128 v[184:187], v146 offset:3072
	s_add_u32 s46, s62, 0x40000
	s_addc_u32 s47, s63, 0
	s_mov_b32 m0, s80
	v_lshl_add_u64 v[228:229], s[46:47], 0, v[138:139]
	ds_read_b128 v[188:191], v177 offset:32768
	ds_read_b128 v[192:195], v177 offset:33792
	ds_read_b128 v[196:199], v177 offset:34816
	ds_read_b128 v[200:203], v177 offset:35840
	ds_read_b128 v[204:207], v177 offset:36864
	ds_read_b128 v[208:211], v177 offset:37888
	ds_read_b128 v[212:215], v177 offset:38912
	ds_read_b128 v[216:219], v177 offset:39936
	global_load_lds_dwordx4 v[228:229], off
	v_lshl_add_u64 v[228:229], s[46:47], 0, v[142:143]
	s_mov_b32 m0, s81
	s_nop 0
	global_load_lds_dwordx4 v[228:229], off
	s_waitcnt vmcnt(8)
	s_waitcnt lgkmcnt(0)
	s_barrier
	s_waitcnt lgkmcnt(0)
	v_mfma_f32_16x16x32_bf16 v[126:129], v[130:133], v[188:191], v[126:129]
	v_mfma_f32_16x16x32_bf16 v[122:125], v[156:159], v[188:191], v[122:125]
	v_mfma_f32_16x16x32_bf16 v[118:121], v[130:133], v[196:199], v[118:121]
	v_mfma_f32_16x16x32_bf16 v[114:117], v[156:159], v[196:199], v[114:117]
	v_mfma_f32_16x16x32_bf16 v[110:113], v[130:133], v[204:207], v[110:113]
	v_mfma_f32_16x16x32_bf16 v[106:109], v[156:159], v[204:207], v[106:109]
	v_mfma_f32_16x16x32_bf16 v[102:105], v[130:133], v[212:215], v[102:105]
	v_mfma_f32_16x16x32_bf16 v[98:101], v[156:159], v[212:215], v[98:101]
	v_mfma_f32_16x16x32_bf16 v[126:129], v[134:137], v[192:195], v[126:129]
	v_mfma_f32_16x16x32_bf16 v[122:125], v[160:163], v[192:195], v[122:125]
	v_mfma_f32_16x16x32_bf16 v[118:121], v[134:137], v[200:203], v[118:121]
	v_mfma_f32_16x16x32_bf16 v[114:117], v[160:163], v[200:203], v[114:117]
	v_mfma_f32_16x16x32_bf16 v[110:113], v[134:137], v[208:211], v[110:113]
	v_mfma_f32_16x16x32_bf16 v[106:109], v[160:163], v[208:211], v[106:109]
	v_mfma_f32_16x16x32_bf16 v[102:105], v[134:137], v[216:219], v[102:105]
	v_mfma_f32_16x16x32_bf16 v[98:101], v[160:163], v[216:219], v[98:101]
	v_mfma_f32_16x16x32_bf16 v[62:65], v[164:167], v[188:191], v[62:65]
	v_mfma_f32_16x16x32_bf16 v[58:61], v[180:183], v[188:191], v[58:61]
	v_mfma_f32_16x16x32_bf16 v[54:57], v[164:167], v[196:199], v[54:57]
	v_mfma_f32_16x16x32_bf16 v[50:53], v[180:183], v[196:199], v[50:53]
	v_mfma_f32_16x16x32_bf16 v[46:49], v[164:167], v[204:207], v[46:49]
	v_mfma_f32_16x16x32_bf16 v[42:45], v[180:183], v[204:207], v[42:45]
	v_mfma_f32_16x16x32_bf16 v[38:41], v[164:167], v[212:215], v[38:41]
	v_mfma_f32_16x16x32_bf16 v[34:37], v[180:183], v[212:215], v[34:37]
	v_mfma_f32_16x16x32_bf16 v[62:65], v[168:171], v[192:195], v[62:65]
	v_mfma_f32_16x16x32_bf16 v[58:61], v[184:187], v[192:195], v[58:61]
	v_mfma_f32_16x16x32_bf16 v[54:57], v[168:171], v[200:203], v[54:57]
	v_mfma_f32_16x16x32_bf16 v[50:53], v[184:187], v[200:203], v[50:53]
	v_mfma_f32_16x16x32_bf16 v[46:49], v[168:171], v[208:211], v[46:49]
	v_mfma_f32_16x16x32_bf16 v[42:45], v[184:187], v[208:211], v[42:45]
	v_mfma_f32_16x16x32_bf16 v[38:41], v[168:171], v[216:219], v[38:41]
	v_mfma_f32_16x16x32_bf16 v[34:37], v[184:187], v[216:219], v[34:37]
	s_barrier
	s_add_i32 s46, s55, s61
	v_lshl_add_u64 v[220:221], v[220:221], 0, s[38:39]
	s_mov_b32 m0, s46
	ds_read_b128 v[188:191], v177 offset:49152
	ds_read_b128 v[192:195], v177 offset:50176
	ds_read_b128 v[196:199], v177 offset:51200
	ds_read_b128 v[200:203], v177 offset:52224
	ds_read_b128 v[204:207], v177 offset:53248
	ds_read_b128 v[208:211], v177 offset:54272
	ds_read_b128 v[212:215], v177 offset:55296
	ds_read_b128 v[216:219], v177 offset:56320
	global_load_lds_dwordx4 v[220:221], off
	s_add_i32 m0, s46, 0x2000
	s_add_u32 s12, s12, 0x40080
	v_lshl_add_u64 v[220:221], v[222:223], 0, s[38:39]
	s_addc_u32 s13, s13, 0
	s_add_i32 s46, s74, s61
	global_load_lds_dwordx4 v[220:221], off
	v_lshl_add_u64 v[220:221], s[12:13], 0, v[140:141]
	s_mov_b32 m0, s46
	s_nop 0
	global_load_lds_dwordx4 v[220:221], off
	v_lshl_add_u64 v[220:221], s[12:13], 0, v[144:145]
	s_add_i32 m0, s46, 0x2000
	s_nop 0
	global_load_lds_dwordx4 v[220:221], off
	v_lshl_add_u64 v[220:221], v[224:225], 0, s[38:39]
	s_mov_b32 m0, s84
	s_nop 0
	global_load_lds_dwordx4 v[220:221], off
	v_lshl_add_u64 v[220:221], v[226:227], 0, s[38:39]
	s_mov_b32 m0, s85
	s_nop 0
	global_load_lds_dwordx4 v[220:221], off
	s_waitcnt vmcnt(8)
	s_waitcnt lgkmcnt(0)
	s_barrier
	s_waitcnt lgkmcnt(0)
	v_mfma_f32_16x16x32_bf16 v[94:97], v[130:133], v[188:191], v[94:97]
	v_mfma_f32_16x16x32_bf16 v[90:93], v[156:159], v[188:191], v[90:93]
	v_mfma_f32_16x16x32_bf16 v[86:89], v[130:133], v[196:199], v[86:89]
	v_mfma_f32_16x16x32_bf16 v[82:85], v[156:159], v[196:199], v[82:85]
	v_mfma_f32_16x16x32_bf16 v[78:81], v[130:133], v[204:207], v[78:81]
	v_mfma_f32_16x16x32_bf16 v[74:77], v[156:159], v[204:207], v[74:77]
	v_mfma_f32_16x16x32_bf16 v[70:73], v[130:133], v[212:215], v[70:73]
	v_mfma_f32_16x16x32_bf16 v[66:69], v[156:159], v[212:215], v[66:69]
	v_mfma_f32_16x16x32_bf16 v[94:97], v[134:137], v[192:195], v[94:97]
	v_mfma_f32_16x16x32_bf16 v[90:93], v[160:163], v[192:195], v[90:93]
	v_mfma_f32_16x16x32_bf16 v[86:89], v[134:137], v[200:203], v[86:89]
	v_mfma_f32_16x16x32_bf16 v[82:85], v[160:163], v[200:203], v[82:85]
	v_mfma_f32_16x16x32_bf16 v[78:81], v[134:137], v[208:211], v[78:81]
	v_mfma_f32_16x16x32_bf16 v[74:77], v[160:163], v[208:211], v[74:77]
	v_mfma_f32_16x16x32_bf16 v[70:73], v[134:137], v[216:219], v[70:73]
	v_mfma_f32_16x16x32_bf16 v[66:69], v[160:163], v[216:219], v[66:69]
	v_mfma_f32_16x16x32_bf16 v[30:33], v[164:167], v[188:191], v[30:33]
	v_mfma_f32_16x16x32_bf16 v[26:29], v[180:183], v[188:191], v[26:29]
	v_mfma_f32_16x16x32_bf16 v[22:25], v[164:167], v[196:199], v[22:25]
	v_mfma_f32_16x16x32_bf16 v[18:21], v[180:183], v[196:199], v[18:21]
	v_mfma_f32_16x16x32_bf16 v[14:17], v[164:167], v[204:207], v[14:17]
	v_mfma_f32_16x16x32_bf16 v[10:13], v[180:183], v[204:207], v[10:13]
	v_mfma_f32_16x16x32_bf16 v[6:9], v[164:167], v[212:215], v[6:9]
	v_mfma_f32_16x16x32_bf16 v[2:5], v[180:183], v[212:215], v[2:5]
	v_mfma_f32_16x16x32_bf16 v[30:33], v[168:171], v[192:195], v[30:33]
	v_mfma_f32_16x16x32_bf16 v[26:29], v[184:187], v[192:195], v[26:29]
	v_mfma_f32_16x16x32_bf16 v[22:25], v[168:171], v[200:203], v[22:25]
	v_mfma_f32_16x16x32_bf16 v[18:21], v[184:187], v[200:203], v[18:21]
	v_mfma_f32_16x16x32_bf16 v[14:17], v[168:171], v[208:211], v[14:17]
	v_mfma_f32_16x16x32_bf16 v[10:13], v[184:187], v[208:211], v[10:13]
	v_mfma_f32_16x16x32_bf16 v[6:9], v[168:171], v[216:219], v[6:9]
	v_mfma_f32_16x16x32_bf16 v[2:5], v[184:187], v[216:219], v[2:5]
	s_add_i32 s45, s45, 2
	s_add_u32 s10, s10, 0x100
	s_addc_u32 s11, s11, 0
	s_add_u32 s16, s16, 0x100
	s_addc_u32 s44, s44, 0
	s_cmp_gt_u32 s45, 13
	s_barrier
	s_cbranch_scc0 .LBB0_590
	s_and_b64 vcc, exec, s[40:41]
	s_cbranch_vccz .LBB0_593
	s_barrier

.LBB0_1097:
	v_add_u32_e32 v158, s79, v161
	ds_read_b128 v[146:149], v158
	ds_read_b128 v[150:153], v158 offset:1024
	ds_read_b128 v[154:157], v158 offset:2048
	ds_read_b128 v[164:167], v158 offset:3072
	v_add_u32_e32 v158, s80, v161
	ds_read_b128 v[168:171], v158
	ds_read_b128 v[172:175], v158 offset:1024
	ds_read_b128 v[176:179], v158 offset:2048
	ds_read_b128 v[180:183], v158 offset:3072
	s_add_u32 s45, s48, 0xfffc0080
	s_addc_u32 s47, s49, -1
	s_cmp_eq_u32 s44, 12
	s_cselect_b32 s53, s41, s47
	s_cselect_b32 s52, s40, s45
	s_cselect_b32 s51, s43, s35
	s_cselect_b32 s50, s42, s31
	v_lshl_add_u64 v[158:159], s[48:49], 0, v[138:139]
	s_add_i32 m0, s58, 0xc000
	ds_read_b128 v[184:187], v163
	ds_read_b128 v[188:191], v163 offset:1024
	ds_read_b128 v[192:195], v163 offset:2048
	ds_read_b128 v[196:199], v163 offset:3072
	ds_read_b128 v[200:203], v163 offset:4096
	ds_read_b128 v[204:207], v163 offset:5120
	ds_read_b128 v[208:211], v163 offset:6144
	ds_read_b128 v[212:215], v163 offset:7168
	global_load_lds_dwordx4 v[158:159], off
	v_lshl_add_u64 v[158:159], s[48:49], 0, v[140:141]
	s_add_i32 m0, s58, 0xe000
	s_nop 0
	global_load_lds_dwordx4 v[158:159], off
	s_waitcnt vmcnt(8)
	s_waitcnt lgkmcnt(0)
	s_barrier
	s_waitcnt lgkmcnt(0)
	v_mfma_f32_16x16x32_bf16 v[126:129], v[146:149], v[184:187], v[126:129]
	v_mfma_f32_16x16x32_bf16 v[122:125], v[154:157], v[184:187], v[122:125]
	v_mfma_f32_16x16x32_bf16 v[118:121], v[146:149], v[192:195], v[118:121]
	v_mfma_f32_16x16x32_bf16 v[114:117], v[154:157], v[192:195], v[114:117]
	v_mfma_f32_16x16x32_bf16 v[110:113], v[146:149], v[200:203], v[110:113]
	v_mfma_f32_16x16x32_bf16 v[106:109], v[154:157], v[200:203], v[106:109]
	v_mfma_f32_16x16x32_bf16 v[102:105], v[146:149], v[208:211], v[102:105]
	v_mfma_f32_16x16x32_bf16 v[98:101], v[154:157], v[208:211], v[98:101]
	v_mfma_f32_16x16x32_bf16 v[126:129], v[150:153], v[188:191], v[126:129]
	v_mfma_f32_16x16x32_bf16 v[122:125], v[164:167], v[188:191], v[122:125]
	v_mfma_f32_16x16x32_bf16 v[118:121], v[150:153], v[196:199], v[118:121]
	v_mfma_f32_16x16x32_bf16 v[114:117], v[164:167], v[196:199], v[114:117]
	v_mfma_f32_16x16x32_bf16 v[110:113], v[150:153], v[204:207], v[110:113]
	v_mfma_f32_16x16x32_bf16 v[106:109], v[164:167], v[204:207], v[106:109]
	v_mfma_f32_16x16x32_bf16 v[102:105], v[150:153], v[212:215], v[102:105]
	v_mfma_f32_16x16x32_bf16 v[98:101], v[164:167], v[212:215], v[98:101]
	v_mfma_f32_16x16x32_bf16 v[94:97], v[168:171], v[184:187], v[94:97]
	v_mfma_f32_16x16x32_bf16 v[90:93], v[176:179], v[184:187], v[90:93]
	v_mfma_f32_16x16x32_bf16 v[86:89], v[168:171], v[192:195], v[86:89]
	v_mfma_f32_16x16x32_bf16 v[82:85], v[176:179], v[192:195], v[82:85]
	v_mfma_f32_16x16x32_bf16 v[78:81], v[168:171], v[200:203], v[78:81]
	v_mfma_f32_16x16x32_bf16 v[74:77], v[176:179], v[200:203], v[74:77]
	v_mfma_f32_16x16x32_bf16 v[70:73], v[168:171], v[208:211], v[70:73]
	v_mfma_f32_16x16x32_bf16 v[66:69], v[176:179], v[208:211], v[66:69]
	v_mfma_f32_16x16x32_bf16 v[94:97], v[172:175], v[188:191], v[94:97]
	v_mfma_f32_16x16x32_bf16 v[90:93], v[180:183], v[188:191], v[90:93]
	v_mfma_f32_16x16x32_bf16 v[86:89], v[172:175], v[196:199], v[86:89]
	v_mfma_f32_16x16x32_bf16 v[82:85], v[180:183], v[196:199], v[82:85]
	v_mfma_f32_16x16x32_bf16 v[78:81], v[172:175], v[204:207], v[78:81]
	v_mfma_f32_16x16x32_bf16 v[74:77], v[180:183], v[204:207], v[74:77]
	v_mfma_f32_16x16x32_bf16 v[70:73], v[172:175], v[212:215], v[70:73]
	v_mfma_f32_16x16x32_bf16 v[66:69], v[180:183], v[212:215], v[66:69]
	s_barrier
	s_add_i32 s45, s79, s57
	v_lshl_add_u64 v[158:159], s[50:51], 0, v[132:133]
	s_mov_b32 m0, s45
	ds_read_b128 v[184:187], v163 offset:16384
	ds_read_b128 v[188:191], v163 offset:17408
	ds_read_b128 v[192:195], v163 offset:18432
	ds_read_b128 v[196:199], v163 offset:19456
	ds_read_b128 v[200:203], v163 offset:20480
	ds_read_b128 v[204:207], v163 offset:21504
	ds_read_b128 v[208:211], v163 offset:22528
	ds_read_b128 v[212:215], v163 offset:23552
	global_load_lds_dwordx4 v[158:159], off
	s_add_i32 m0, s45, 0x2000
	s_add_u32 s84, s50, 0x40000
	v_lshl_add_u64 v[216:217], s[50:51], 0, v[136:137]
	s_addc_u32 s85, s51, 0
	s_add_i32 s45, s80, s57
	global_load_lds_dwordx4 v[216:217], off
	v_lshl_add_u64 v[218:219], s[84:85], 0, v[132:133]
	s_mov_b32 m0, s45
	v_lshl_add_u64 v[220:221], s[52:53], 0, v[134:135]
	global_load_lds_dwordx4 v[218:219], off
	v_lshl_add_u64 v[218:219], s[84:85], 0, v[136:137]
	s_add_i32 m0, s45, 0x2000
	s_nop 0
	global_load_lds_dwordx4 v[218:219], off
	v_lshl_add_u64 v[218:219], s[52:53], 0, v[130:131]
	s_mov_b32 m0, s58
	s_nop 0
	global_load_lds_dwordx4 v[218:219], off
	s_mov_b32 m0, s59
	s_nop 0
	global_load_lds_dwordx4 v[220:221], off
	s_waitcnt vmcnt(8)
	s_waitcnt lgkmcnt(0)
	s_barrier
	s_waitcnt lgkmcnt(0)
	v_mfma_f32_16x16x32_bf16 v[62:65], v[146:149], v[184:187], v[62:65]
	v_mfma_f32_16x16x32_bf16 v[58:61], v[154:157], v[184:187], v[58:61]
	v_mfma_f32_16x16x32_bf16 v[54:57], v[146:149], v[192:195], v[54:57]
	v_mfma_f32_16x16x32_bf16 v[50:53], v[154:157], v[192:195], v[50:53]
	v_mfma_f32_16x16x32_bf16 v[46:49], v[146:149], v[200:203], v[46:49]
	v_mfma_f32_16x16x32_bf16 v[42:45], v[154:157], v[200:203], v[42:45]
	v_mfma_f32_16x16x32_bf16 v[38:41], v[146:149], v[208:211], v[38:41]
	v_mfma_f32_16x16x32_bf16 v[34:37], v[154:157], v[208:211], v[34:37]
	v_mfma_f32_16x16x32_bf16 v[62:65], v[150:153], v[188:191], v[62:65]
	v_mfma_f32_16x16x32_bf16 v[58:61], v[164:167], v[188:191], v[58:61]
	v_mfma_f32_16x16x32_bf16 v[54:57], v[150:153], v[196:199], v[54:57]
	v_mfma_f32_16x16x32_bf16 v[50:53], v[164:167], v[196:199], v[50:53]
	v_mfma_f32_16x16x32_bf16 v[46:49], v[150:153], v[204:207], v[46:49]
	v_mfma_f32_16x16x32_bf16 v[42:45], v[164:167], v[204:207], v[42:45]
	v_mfma_f32_16x16x32_bf16 v[38:41], v[150:153], v[212:215], v[38:41]
	v_mfma_f32_16x16x32_bf16 v[34:37], v[164:167], v[212:215], v[34:37]
	v_mfma_f32_16x16x32_bf16 v[30:33], v[168:171], v[184:187], v[30:33]
	v_mfma_f32_16x16x32_bf16 v[26:29], v[176:179], v[184:187], v[26:29]
	v_mfma_f32_16x16x32_bf16 v[22:25], v[168:171], v[192:195], v[22:25]
	v_mfma_f32_16x16x32_bf16 v[18:21], v[176:179], v[192:195], v[18:21]
	v_mfma_f32_16x16x32_bf16 v[14:17], v[168:171], v[200:203], v[14:17]
	v_mfma_f32_16x16x32_bf16 v[10:13], v[176:179], v[200:203], v[10:13]
	v_mfma_f32_16x16x32_bf16 v[6:9], v[168:171], v[208:211], v[6:9]
	v_mfma_f32_16x16x32_bf16 v[2:5], v[176:179], v[208:211], v[2:5]
	v_mfma_f32_16x16x32_bf16 v[30:33], v[172:175], v[188:191], v[30:33]
	v_mfma_f32_16x16x32_bf16 v[26:29], v[180:183], v[188:191], v[26:29]
	v_mfma_f32_16x16x32_bf16 v[22:25], v[172:175], v[196:199], v[22:25]
	v_mfma_f32_16x16x32_bf16 v[18:21], v[180:183], v[196:199], v[18:21]
	v_mfma_f32_16x16x32_bf16 v[14:17], v[172:175], v[204:207], v[14:17]
	v_mfma_f32_16x16x32_bf16 v[10:13], v[180:183], v[204:207], v[10:13]
	v_mfma_f32_16x16x32_bf16 v[6:9], v[172:175], v[212:215], v[6:9]
	v_mfma_f32_16x16x32_bf16 v[2:5], v[180:183], v[212:215], v[2:5]
	s_barrier
	s_add_i32 s45, 0, 0x18000
	s_add_i32 s47, 0, 0x1c000
	v_add_u32_e32 v164, s45, v161
	v_add_u32_e32 v180, s47, v161
	ds_read_b128 v[146:149], v164
	ds_read_b128 v[150:153], v164 offset:1024
	ds_read_b128 v[154:157], v164 offset:2048
	ds_read_b128 v[164:167], v164 offset:3072
	ds_read_b128 v[168:171], v180
	ds_read_b128 v[172:175], v180 offset:1024
	ds_read_b128 v[176:179], v180 offset:2048
	ds_read_b128 v[180:183], v180 offset:3072
	s_add_u32 s52, s52, 0x40000
	s_addc_u32 s53, s53, 0
	s_mov_b32 m0, s60
	v_lshl_add_u64 v[222:223], s[52:53], 0, v[130:131]
	ds_read_b128 v[184:187], v163 offset:32768
	ds_read_b128 v[188:191], v163 offset:33792
	ds_read_b128 v[192:195], v163 offset:34816
	ds_read_b128 v[196:199], v163 offset:35840
	ds_read_b128 v[200:203], v163 offset:36864
	ds_read_b128 v[204:207], v163 offset:37888
	ds_read_b128 v[208:211], v163 offset:38912
	ds_read_b128 v[212:215], v163 offset:39936
	global_load_lds_dwordx4 v[222:223], off
	v_lshl_add_u64 v[222:223], s[52:53], 0, v[134:135]
	s_mov_b32 m0, s61
	s_nop 0
	global_load_lds_dwordx4 v[222:223], off
	s_waitcnt vmcnt(8)
	s_waitcnt lgkmcnt(0)
	s_barrier
	s_waitcnt lgkmcnt(0)
	v_mfma_f32_16x16x32_bf16 v[126:129], v[146:149], v[184:187], v[126:129]
	v_mfma_f32_16x16x32_bf16 v[122:125], v[154:157], v[184:187], v[122:125]
	v_mfma_f32_16x16x32_bf16 v[118:121], v[146:149], v[192:195], v[118:121]
	v_mfma_f32_16x16x32_bf16 v[114:117], v[154:157], v[192:195], v[114:117]
	v_mfma_f32_16x16x32_bf16 v[110:113], v[146:149], v[200:203], v[110:113]
	v_mfma_f32_16x16x32_bf16 v[106:109], v[154:157], v[200:203], v[106:109]
	v_mfma_f32_16x16x32_bf16 v[102:105], v[146:149], v[208:211], v[102:105]
	v_mfma_f32_16x16x32_bf16 v[98:101], v[154:157], v[208:211], v[98:101]
	v_mfma_f32_16x16x32_bf16 v[126:129], v[150:153], v[188:191], v[126:129]
	v_mfma_f32_16x16x32_bf16 v[122:125], v[164:167], v[188:191], v[122:125]
	v_mfma_f32_16x16x32_bf16 v[118:121], v[150:153], v[196:199], v[118:121]
	v_mfma_f32_16x16x32_bf16 v[114:117], v[164:167], v[196:199], v[114:117]
	v_mfma_f32_16x16x32_bf16 v[110:113], v[150:153], v[204:207], v[110:113]
	v_mfma_f32_16x16x32_bf16 v[106:109], v[164:167], v[204:207], v[106:109]
	v_mfma_f32_16x16x32_bf16 v[102:105], v[150:153], v[212:215], v[102:105]
	v_mfma_f32_16x16x32_bf16 v[98:101], v[164:167], v[212:215], v[98:101]
	v_mfma_f32_16x16x32_bf16 v[94:97], v[168:171], v[184:187], v[94:97]
	v_mfma_f32_16x16x32_bf16 v[90:93], v[176:179], v[184:187], v[90:93]
	v_mfma_f32_16x16x32_bf16 v[86:89], v[168:171], v[192:195], v[86:89]
	v_mfma_f32_16x16x32_bf16 v[82:85], v[176:179], v[192:195], v[82:85]
	v_mfma_f32_16x16x32_bf16 v[78:81], v[168:171], v[200:203], v[78:81]
	v_mfma_f32_16x16x32_bf16 v[74:77], v[176:179], v[200:203], v[74:77]
	v_mfma_f32_16x16x32_bf16 v[70:73], v[168:171], v[208:211], v[70:73]
	v_mfma_f32_16x16x32_bf16 v[66:69], v[176:179], v[208:211], v[66:69]
	v_mfma_f32_16x16x32_bf16 v[94:97], v[172:175], v[188:191], v[94:97]
	v_mfma_f32_16x16x32_bf16 v[90:93], v[180:183], v[188:191], v[90:93]
	v_mfma_f32_16x16x32_bf16 v[86:89], v[172:175], v[196:199], v[86:89]
	v_mfma_f32_16x16x32_bf16 v[82:85], v[180:183], v[196:199], v[82:85]
	v_mfma_f32_16x16x32_bf16 v[78:81], v[172:175], v[204:207], v[78:81]
	v_mfma_f32_16x16x32_bf16 v[74:77], v[180:183], v[204:207], v[74:77]
	v_mfma_f32_16x16x32_bf16 v[70:73], v[172:175], v[212:215], v[70:73]
	v_mfma_f32_16x16x32_bf16 v[66:69], v[180:183], v[212:215], v[66:69]
	s_barrier
	s_add_i32 s45, s45, s57
	v_lshl_add_u64 v[158:159], v[158:159], 0, s[18:19]
	s_mov_b32 m0, s45
	ds_read_b128 v[184:187], v163 offset:49152
	ds_read_b128 v[188:191], v163 offset:50176
	ds_read_b128 v[192:195], v163 offset:51200
	ds_read_b128 v[196:199], v163 offset:52224
	ds_read_b128 v[200:203], v163 offset:53248
	ds_read_b128 v[204:207], v163 offset:54272
	ds_read_b128 v[208:211], v163 offset:55296
	ds_read_b128 v[212:215], v163 offset:56320
	global_load_lds_dwordx4 v[158:159], off
	s_add_i32 m0, s45, 0x2000
	s_add_u32 s50, s50, 0x40080
	v_lshl_add_u64 v[158:159], v[216:217], 0, s[18:19]
	s_addc_u32 s51, s51, 0
	s_add_i32 s45, s47, s57
	global_load_lds_dwordx4 v[158:159], off
	v_lshl_add_u64 v[158:159], s[50:51], 0, v[132:133]
	s_mov_b32 m0, s45
	s_nop 0
	global_load_lds_dwordx4 v[158:159], off
	v_lshl_add_u64 v[158:159], s[50:51], 0, v[136:137]
	s_add_i32 m0, s45, 0x2000
	s_nop 0
	global_load_lds_dwordx4 v[158:159], off
	v_lshl_add_u64 v[158:159], v[218:219], 0, s[18:19]
	s_mov_b32 m0, s77
	s_nop 0
	global_load_lds_dwordx4 v[158:159], off
	v_lshl_add_u64 v[158:159], v[220:221], 0, s[18:19]
	s_mov_b32 m0, s78
	s_nop 0
	global_load_lds_dwordx4 v[158:159], off
	s_waitcnt vmcnt(8)
	s_waitcnt lgkmcnt(0)
	s_barrier
	s_waitcnt lgkmcnt(0)
	v_mfma_f32_16x16x32_bf16 v[62:65], v[146:149], v[184:187], v[62:65]
	v_mfma_f32_16x16x32_bf16 v[58:61], v[154:157], v[184:187], v[58:61]
	v_mfma_f32_16x16x32_bf16 v[54:57], v[146:149], v[192:195], v[54:57]
	v_mfma_f32_16x16x32_bf16 v[50:53], v[154:157], v[192:195], v[50:53]
	v_mfma_f32_16x16x32_bf16 v[46:49], v[146:149], v[200:203], v[46:49]
	v_mfma_f32_16x16x32_bf16 v[42:45], v[154:157], v[200:203], v[42:45]
	v_mfma_f32_16x16x32_bf16 v[38:41], v[146:149], v[208:211], v[38:41]
	v_mfma_f32_16x16x32_bf16 v[34:37], v[154:157], v[208:211], v[34:37]
	v_mfma_f32_16x16x32_bf16 v[62:65], v[150:153], v[188:191], v[62:65]
	v_mfma_f32_16x16x32_bf16 v[58:61], v[164:167], v[188:191], v[58:61]
	v_mfma_f32_16x16x32_bf16 v[54:57], v[150:153], v[196:199], v[54:57]
	v_mfma_f32_16x16x32_bf16 v[50:53], v[164:167], v[196:199], v[50:53]
	v_mfma_f32_16x16x32_bf16 v[46:49], v[150:153], v[204:207], v[46:49]
	v_mfma_f32_16x16x32_bf16 v[42:45], v[164:167], v[204:207], v[42:45]
	v_mfma_f32_16x16x32_bf16 v[38:41], v[150:153], v[212:215], v[38:41]
	v_mfma_f32_16x16x32_bf16 v[34:37], v[164:167], v[212:215], v[34:37]
	v_mfma_f32_16x16x32_bf16 v[30:33], v[168:171], v[184:187], v[30:33]
	v_mfma_f32_16x16x32_bf16 v[26:29], v[176:179], v[184:187], v[26:29]
	v_mfma_f32_16x16x32_bf16 v[22:25], v[168:171], v[192:195], v[22:25]
	v_mfma_f32_16x16x32_bf16 v[18:21], v[176:179], v[192:195], v[18:21]
	v_mfma_f32_16x16x32_bf16 v[14:17], v[168:171], v[200:203], v[14:17]
	v_mfma_f32_16x16x32_bf16 v[10:13], v[176:179], v[200:203], v[10:13]
	v_mfma_f32_16x16x32_bf16 v[6:9], v[168:171], v[208:211], v[6:9]
	v_mfma_f32_16x16x32_bf16 v[2:5], v[176:179], v[208:211], v[2:5]
	v_mfma_f32_16x16x32_bf16 v[30:33], v[172:175], v[188:191], v[30:33]
	v_mfma_f32_16x16x32_bf16 v[26:29], v[180:183], v[188:191], v[26:29]
	v_mfma_f32_16x16x32_bf16 v[22:25], v[172:175], v[196:199], v[22:25]
	v_mfma_f32_16x16x32_bf16 v[18:21], v[180:183], v[196:199], v[18:21]
	v_mfma_f32_16x16x32_bf16 v[14:17], v[172:175], v[204:207], v[14:17]
	v_mfma_f32_16x16x32_bf16 v[10:13], v[180:183], v[204:207], v[10:13]
	v_mfma_f32_16x16x32_bf16 v[6:9], v[172:175], v[212:215], v[6:9]
	v_mfma_f32_16x16x32_bf16 v[2:5], v[180:183], v[212:215], v[2:5]
	s_add_i32 s44, s44, 2
	s_add_u32 s48, s48, 0x100
	s_addc_u32 s49, s49, 0
	s_add_u32 s31, s31, 0x100
	s_addc_u32 s35, s35, 0
	s_cmp_gt_u32 s44, 13
	s_barrier
	s_cbranch_scc0 .LBB0_1097
	s_and_b64 vcc, exec, s[20:21]
	s_cbranch_vccz .LBB0_1100
	s_barrier

.LBB0_1254:
	ds_read_b128 v[130:133], v167
	ds_read_b128 v[134:137], v167 offset:1024
	ds_read_b128 v[156:159], v167 offset:2048
	ds_read_b128 v[160:163], v167 offset:3072
	ds_read_b128 v[170:173], v168
	ds_read_b128 v[174:177], v168 offset:1024
	ds_read_b128 v[178:181], v168 offset:2048
	ds_read_b128 v[182:185], v168 offset:3072
	s_add_u32 s14, s12, 0xfffc0080
	s_addc_u32 s15, s13, -1
	s_cmp_eq_u32 s39, 12
	s_cselect_b32 s17, s9, s15
	s_cselect_b32 s16, s8, s14
	s_cselect_b32 s15, s11, s19
	s_cselect_b32 s14, s10, s7
	v_lshl_add_u64 v[218:219], s[12:13], 0, v[148:149]
	s_add_i32 m0, s51, 0xc000
	ds_read_b128 v[186:189], v169
	ds_read_b128 v[190:193], v169 offset:1024
	ds_read_b128 v[194:197], v169 offset:2048
	ds_read_b128 v[198:201], v169 offset:3072
	ds_read_b128 v[202:205], v169 offset:4096
	ds_read_b128 v[206:209], v169 offset:5120
	ds_read_b128 v[210:213], v169 offset:6144
	ds_read_b128 v[214:217], v169 offset:7168
	global_load_lds_dwordx4 v[218:219], off
	v_lshl_add_u64 v[218:219], s[12:13], 0, v[150:151]
	s_add_i32 m0, s51, 0xe000
	s_nop 0
	global_load_lds_dwordx4 v[218:219], off
	s_waitcnt vmcnt(8)
	s_waitcnt lgkmcnt(0)
	s_barrier
	s_waitcnt lgkmcnt(0)
	v_mfma_f32_16x16x32_bf16 v[126:129], v[130:133], v[186:189], v[126:129]
	v_mfma_f32_16x16x32_bf16 v[122:125], v[156:159], v[186:189], v[122:125]
	v_mfma_f32_16x16x32_bf16 v[118:121], v[130:133], v[194:197], v[118:121]
	v_mfma_f32_16x16x32_bf16 v[114:117], v[156:159], v[194:197], v[114:117]
	v_mfma_f32_16x16x32_bf16 v[110:113], v[130:133], v[202:205], v[110:113]
	v_mfma_f32_16x16x32_bf16 v[106:109], v[156:159], v[202:205], v[106:109]
	v_mfma_f32_16x16x32_bf16 v[102:105], v[130:133], v[210:213], v[102:105]
	v_mfma_f32_16x16x32_bf16 v[98:101], v[156:159], v[210:213], v[98:101]
	v_mfma_f32_16x16x32_bf16 v[126:129], v[134:137], v[190:193], v[126:129]
	v_mfma_f32_16x16x32_bf16 v[122:125], v[160:163], v[190:193], v[122:125]
	v_mfma_f32_16x16x32_bf16 v[118:121], v[134:137], v[198:201], v[118:121]
	v_mfma_f32_16x16x32_bf16 v[114:117], v[160:163], v[198:201], v[114:117]
	v_mfma_f32_16x16x32_bf16 v[110:113], v[134:137], v[206:209], v[110:113]
	v_mfma_f32_16x16x32_bf16 v[106:109], v[160:163], v[206:209], v[106:109]
	v_mfma_f32_16x16x32_bf16 v[102:105], v[134:137], v[214:217], v[102:105]
	v_mfma_f32_16x16x32_bf16 v[98:101], v[160:163], v[214:217], v[98:101]
	v_mfma_f32_16x16x32_bf16 v[62:65], v[170:173], v[186:189], v[62:65]
	v_mfma_f32_16x16x32_bf16 v[58:61], v[178:181], v[186:189], v[58:61]
	v_mfma_f32_16x16x32_bf16 v[54:57], v[170:173], v[194:197], v[54:57]
	v_mfma_f32_16x16x32_bf16 v[50:53], v[178:181], v[194:197], v[50:53]
	v_mfma_f32_16x16x32_bf16 v[46:49], v[170:173], v[202:205], v[46:49]
	v_mfma_f32_16x16x32_bf16 v[42:45], v[178:181], v[202:205], v[42:45]
	v_mfma_f32_16x16x32_bf16 v[38:41], v[170:173], v[210:213], v[38:41]
	v_mfma_f32_16x16x32_bf16 v[34:37], v[178:181], v[210:213], v[34:37]
	v_mfma_f32_16x16x32_bf16 v[62:65], v[174:177], v[190:193], v[62:65]
	v_mfma_f32_16x16x32_bf16 v[58:61], v[182:185], v[190:193], v[58:61]
	v_mfma_f32_16x16x32_bf16 v[54:57], v[174:177], v[198:201], v[54:57]
	v_mfma_f32_16x16x32_bf16 v[50:53], v[182:185], v[198:201], v[50:53]
	v_mfma_f32_16x16x32_bf16 v[46:49], v[174:177], v[206:209], v[46:49]
	v_mfma_f32_16x16x32_bf16 v[42:45], v[182:185], v[206:209], v[42:45]
	v_mfma_f32_16x16x32_bf16 v[38:41], v[174:177], v[214:217], v[38:41]
	v_mfma_f32_16x16x32_bf16 v[34:37], v[182:185], v[214:217], v[34:37]
	s_barrier
	s_add_i32 s41, s74, s50
	v_lshl_add_u64 v[218:219], s[14:15], 0, v[140:141]
	s_mov_b32 m0, s41
	ds_read_b128 v[186:189], v169 offset:16384
	ds_read_b128 v[190:193], v169 offset:17408
	ds_read_b128 v[194:197], v169 offset:18432
	ds_read_b128 v[198:201], v169 offset:19456
	ds_read_b128 v[202:205], v169 offset:20480
	ds_read_b128 v[206:209], v169 offset:21504
	ds_read_b128 v[210:213], v169 offset:22528
	ds_read_b128 v[214:217], v169 offset:23552
	global_load_lds_dwordx4 v[218:219], off
	s_add_i32 m0, s41, 0x2000
	s_add_u32 s44, s14, 0x40000
	v_lshl_add_u64 v[220:221], s[14:15], 0, v[144:145]
	s_addc_u32 s45, s15, 0
	s_add_i32 s41, s75, s50
	global_load_lds_dwordx4 v[220:221], off
	v_lshl_add_u64 v[222:223], s[44:45], 0, v[140:141]
	s_mov_b32 m0, s41
	v_lshl_add_u64 v[224:225], s[16:17], 0, v[142:143]
	global_load_lds_dwordx4 v[222:223], off
	v_lshl_add_u64 v[222:223], s[44:45], 0, v[144:145]
	s_add_i32 m0, s41, 0x2000
	s_nop 0
	global_load_lds_dwordx4 v[222:223], off
	v_lshl_add_u64 v[222:223], s[16:17], 0, v[138:139]
	s_mov_b32 m0, s51
	s_nop 0
	global_load_lds_dwordx4 v[222:223], off
	s_mov_b32 m0, s52
	s_nop 0
	global_load_lds_dwordx4 v[224:225], off
	s_waitcnt vmcnt(8)
	s_waitcnt lgkmcnt(0)
	s_barrier
	s_waitcnt lgkmcnt(0)
	v_mfma_f32_16x16x32_bf16 v[94:97], v[130:133], v[186:189], v[94:97]
	v_mfma_f32_16x16x32_bf16 v[90:93], v[156:159], v[186:189], v[90:93]
	v_mfma_f32_16x16x32_bf16 v[86:89], v[130:133], v[194:197], v[86:89]
	v_mfma_f32_16x16x32_bf16 v[82:85], v[156:159], v[194:197], v[82:85]
	v_mfma_f32_16x16x32_bf16 v[78:81], v[130:133], v[202:205], v[78:81]
	v_mfma_f32_16x16x32_bf16 v[74:77], v[156:159], v[202:205], v[74:77]
	v_mfma_f32_16x16x32_bf16 v[70:73], v[130:133], v[210:213], v[70:73]
	v_mfma_f32_16x16x32_bf16 v[66:69], v[156:159], v[210:213], v[66:69]
	v_mfma_f32_16x16x32_bf16 v[94:97], v[134:137], v[190:193], v[94:97]
	v_mfma_f32_16x16x32_bf16 v[90:93], v[160:163], v[190:193], v[90:93]
	v_mfma_f32_16x16x32_bf16 v[86:89], v[134:137], v[198:201], v[86:89]
	v_mfma_f32_16x16x32_bf16 v[82:85], v[160:163], v[198:201], v[82:85]
	v_mfma_f32_16x16x32_bf16 v[78:81], v[134:137], v[206:209], v[78:81]
	v_mfma_f32_16x16x32_bf16 v[74:77], v[160:163], v[206:209], v[74:77]
	v_mfma_f32_16x16x32_bf16 v[70:73], v[134:137], v[214:217], v[70:73]
	v_mfma_f32_16x16x32_bf16 v[66:69], v[160:163], v[214:217], v[66:69]
	v_mfma_f32_16x16x32_bf16 v[30:33], v[170:173], v[186:189], v[30:33]
	v_mfma_f32_16x16x32_bf16 v[26:29], v[178:181], v[186:189], v[26:29]
	v_mfma_f32_16x16x32_bf16 v[22:25], v[170:173], v[194:197], v[22:25]
	v_mfma_f32_16x16x32_bf16 v[18:21], v[178:181], v[194:197], v[18:21]
	v_mfma_f32_16x16x32_bf16 v[14:17], v[170:173], v[202:205], v[14:17]
	v_mfma_f32_16x16x32_bf16 v[10:13], v[178:181], v[202:205], v[10:13]
	v_mfma_f32_16x16x32_bf16 v[6:9], v[170:173], v[210:213], v[6:9]
	v_mfma_f32_16x16x32_bf16 v[2:5], v[178:181], v[210:213], v[2:5]
	v_mfma_f32_16x16x32_bf16 v[30:33], v[174:177], v[190:193], v[30:33]
	v_mfma_f32_16x16x32_bf16 v[26:29], v[182:185], v[190:193], v[26:29]
	v_mfma_f32_16x16x32_bf16 v[22:25], v[174:177], v[198:201], v[22:25]
	v_mfma_f32_16x16x32_bf16 v[18:21], v[182:185], v[198:201], v[18:21]
	v_mfma_f32_16x16x32_bf16 v[14:17], v[174:177], v[206:209], v[14:17]
	v_mfma_f32_16x16x32_bf16 v[10:13], v[182:185], v[206:209], v[10:13]
	v_mfma_f32_16x16x32_bf16 v[6:9], v[174:177], v[214:217], v[6:9]
	v_mfma_f32_16x16x32_bf16 v[2:5], v[182:185], v[214:217], v[2:5]
	s_barrier
	s_add_i32 s41, 0, 0x18000
	v_add_u32_e32 v146, s41, v165
	s_add_i32 s44, 0, 0x1c000
	ds_read_b128 v[130:133], v146
	ds_read_b128 v[134:137], v146 offset:1024
	ds_read_b128 v[156:159], v146 offset:2048
	ds_read_b128 v[160:163], v146 offset:3072
	v_add_u32_e32 v146, s44, v165
	ds_read_b128 v[170:173], v146
	ds_read_b128 v[174:177], v146 offset:1024
	ds_read_b128 v[178:181], v146 offset:2048
	ds_read_b128 v[182:185], v146 offset:3072
	s_add_u32 s16, s16, 0x40000
	s_addc_u32 s17, s17, 0
	s_mov_b32 m0, s53
	v_lshl_add_u64 v[226:227], s[16:17], 0, v[138:139]
	ds_read_b128 v[186:189], v169 offset:32768
	ds_read_b128 v[190:193], v169 offset:33792
	ds_read_b128 v[194:197], v169 offset:34816
	ds_read_b128 v[198:201], v169 offset:35840
	ds_read_b128 v[202:205], v169 offset:36864
	ds_read_b128 v[206:209], v169 offset:37888
	ds_read_b128 v[210:213], v169 offset:38912
	ds_read_b128 v[214:217], v169 offset:39936
	global_load_lds_dwordx4 v[226:227], off
	v_lshl_add_u64 v[226:227], s[16:17], 0, v[142:143]
	s_mov_b32 m0, s54
	s_nop 0
	global_load_lds_dwordx4 v[226:227], off
	s_waitcnt vmcnt(8)
	s_waitcnt lgkmcnt(0)
	s_barrier
	s_waitcnt lgkmcnt(0)
	v_mfma_f32_16x16x32_bf16 v[126:129], v[130:133], v[186:189], v[126:129]
	v_mfma_f32_16x16x32_bf16 v[122:125], v[156:159], v[186:189], v[122:125]
	v_mfma_f32_16x16x32_bf16 v[118:121], v[130:133], v[194:197], v[118:121]
	v_mfma_f32_16x16x32_bf16 v[114:117], v[156:159], v[194:197], v[114:117]
	v_mfma_f32_16x16x32_bf16 v[110:113], v[130:133], v[202:205], v[110:113]
	v_mfma_f32_16x16x32_bf16 v[106:109], v[156:159], v[202:205], v[106:109]
	v_mfma_f32_16x16x32_bf16 v[102:105], v[130:133], v[210:213], v[102:105]
	v_mfma_f32_16x16x32_bf16 v[98:101], v[156:159], v[210:213], v[98:101]
	v_mfma_f32_16x16x32_bf16 v[126:129], v[134:137], v[190:193], v[126:129]
	v_mfma_f32_16x16x32_bf16 v[122:125], v[160:163], v[190:193], v[122:125]
	v_mfma_f32_16x16x32_bf16 v[118:121], v[134:137], v[198:201], v[118:121]
	v_mfma_f32_16x16x32_bf16 v[114:117], v[160:163], v[198:201], v[114:117]
	v_mfma_f32_16x16x32_bf16 v[110:113], v[134:137], v[206:209], v[110:113]
	v_mfma_f32_16x16x32_bf16 v[106:109], v[160:163], v[206:209], v[106:109]
	v_mfma_f32_16x16x32_bf16 v[102:105], v[134:137], v[214:217], v[102:105]
	v_mfma_f32_16x16x32_bf16 v[98:101], v[160:163], v[214:217], v[98:101]
	v_mfma_f32_16x16x32_bf16 v[62:65], v[170:173], v[186:189], v[62:65]
	v_mfma_f32_16x16x32_bf16 v[58:61], v[178:181], v[186:189], v[58:61]
	v_mfma_f32_16x16x32_bf16 v[54:57], v[170:173], v[194:197], v[54:57]
	v_mfma_f32_16x16x32_bf16 v[50:53], v[178:181], v[194:197], v[50:53]
	v_mfma_f32_16x16x32_bf16 v[46:49], v[170:173], v[202:205], v[46:49]
	v_mfma_f32_16x16x32_bf16 v[42:45], v[178:181], v[202:205], v[42:45]
	v_mfma_f32_16x16x32_bf16 v[38:41], v[170:173], v[210:213], v[38:41]
	v_mfma_f32_16x16x32_bf16 v[34:37], v[178:181], v[210:213], v[34:37]
	v_mfma_f32_16x16x32_bf16 v[62:65], v[174:177], v[190:193], v[62:65]
	v_mfma_f32_16x16x32_bf16 v[58:61], v[182:185], v[190:193], v[58:61]
	v_mfma_f32_16x16x32_bf16 v[54:57], v[174:177], v[198:201], v[54:57]
	v_mfma_f32_16x16x32_bf16 v[50:53], v[182:185], v[198:201], v[50:53]
	v_mfma_f32_16x16x32_bf16 v[46:49], v[174:177], v[206:209], v[46:49]
	v_mfma_f32_16x16x32_bf16 v[42:45], v[182:185], v[206:209], v[42:45]
	v_mfma_f32_16x16x32_bf16 v[38:41], v[174:177], v[214:217], v[38:41]
	v_mfma_f32_16x16x32_bf16 v[34:37], v[182:185], v[214:217], v[34:37]
	s_barrier
	s_add_i32 s16, s41, s50
	v_lshl_add_u64 v[218:219], v[218:219], 0, s[30:31]
	s_mov_b32 m0, s16
	ds_read_b128 v[186:189], v169 offset:49152
	ds_read_b128 v[190:193], v169 offset:50176
	ds_read_b128 v[194:197], v169 offset:51200
	ds_read_b128 v[198:201], v169 offset:52224
	ds_read_b128 v[202:205], v169 offset:53248
	ds_read_b128 v[206:209], v169 offset:54272
	ds_read_b128 v[210:213], v169 offset:55296
	ds_read_b128 v[214:217], v169 offset:56320
	global_load_lds_dwordx4 v[218:219], off
	s_add_i32 m0, s16, 0x2000
	s_add_u32 s14, s14, 0x40080
	v_lshl_add_u64 v[218:219], v[220:221], 0, s[30:31]
	s_addc_u32 s15, s15, 0
	s_add_i32 s16, s44, s50
	global_load_lds_dwordx4 v[218:219], off
	v_lshl_add_u64 v[218:219], s[14:15], 0, v[140:141]
	s_mov_b32 m0, s16
	s_nop 0
	global_load_lds_dwordx4 v[218:219], off
	v_lshl_add_u64 v[218:219], s[14:15], 0, v[144:145]
	s_add_i32 m0, s16, 0x2000
	s_nop 0
	global_load_lds_dwordx4 v[218:219], off
	v_lshl_add_u64 v[218:219], v[222:223], 0, s[30:31]
	s_mov_b32 m0, s61
	s_nop 0
	global_load_lds_dwordx4 v[218:219], off
	v_lshl_add_u64 v[218:219], v[224:225], 0, s[30:31]
	s_mov_b32 m0, s62
	s_nop 0
	global_load_lds_dwordx4 v[218:219], off
	s_waitcnt vmcnt(8)
	s_waitcnt lgkmcnt(0)
	s_barrier
	s_waitcnt lgkmcnt(0)
	v_mfma_f32_16x16x32_bf16 v[94:97], v[130:133], v[186:189], v[94:97]
	v_mfma_f32_16x16x32_bf16 v[90:93], v[156:159], v[186:189], v[90:93]
	v_mfma_f32_16x16x32_bf16 v[86:89], v[130:133], v[194:197], v[86:89]
	v_mfma_f32_16x16x32_bf16 v[82:85], v[156:159], v[194:197], v[82:85]
	v_mfma_f32_16x16x32_bf16 v[78:81], v[130:133], v[202:205], v[78:81]
	v_mfma_f32_16x16x32_bf16 v[74:77], v[156:159], v[202:205], v[74:77]
	v_mfma_f32_16x16x32_bf16 v[70:73], v[130:133], v[210:213], v[70:73]
	v_mfma_f32_16x16x32_bf16 v[66:69], v[156:159], v[210:213], v[66:69]
	v_mfma_f32_16x16x32_bf16 v[94:97], v[134:137], v[190:193], v[94:97]
	v_mfma_f32_16x16x32_bf16 v[90:93], v[160:163], v[190:193], v[90:93]
	v_mfma_f32_16x16x32_bf16 v[86:89], v[134:137], v[198:201], v[86:89]
	v_mfma_f32_16x16x32_bf16 v[82:85], v[160:163], v[198:201], v[82:85]
	v_mfma_f32_16x16x32_bf16 v[78:81], v[134:137], v[206:209], v[78:81]
	v_mfma_f32_16x16x32_bf16 v[74:77], v[160:163], v[206:209], v[74:77]
	v_mfma_f32_16x16x32_bf16 v[70:73], v[134:137], v[214:217], v[70:73]
	v_mfma_f32_16x16x32_bf16 v[66:69], v[160:163], v[214:217], v[66:69]
	v_mfma_f32_16x16x32_bf16 v[30:33], v[170:173], v[186:189], v[30:33]
	v_mfma_f32_16x16x32_bf16 v[26:29], v[178:181], v[186:189], v[26:29]
	v_mfma_f32_16x16x32_bf16 v[22:25], v[170:173], v[194:197], v[22:25]
	v_mfma_f32_16x16x32_bf16 v[18:21], v[178:181], v[194:197], v[18:21]
	v_mfma_f32_16x16x32_bf16 v[14:17], v[170:173], v[202:205], v[14:17]
	v_mfma_f32_16x16x32_bf16 v[10:13], v[178:181], v[202:205], v[10:13]
	v_mfma_f32_16x16x32_bf16 v[6:9], v[170:173], v[210:213], v[6:9]
	v_mfma_f32_16x16x32_bf16 v[2:5], v[178:181], v[210:213], v[2:5]
	v_mfma_f32_16x16x32_bf16 v[30:33], v[174:177], v[190:193], v[30:33]
	v_mfma_f32_16x16x32_bf16 v[26:29], v[182:185], v[190:193], v[26:29]
	v_mfma_f32_16x16x32_bf16 v[22:25], v[174:177], v[198:201], v[22:25]
	v_mfma_f32_16x16x32_bf16 v[18:21], v[182:185], v[198:201], v[18:21]
	v_mfma_f32_16x16x32_bf16 v[14:17], v[174:177], v[206:209], v[14:17]
	v_mfma_f32_16x16x32_bf16 v[10:13], v[182:185], v[206:209], v[10:13]
	v_mfma_f32_16x16x32_bf16 v[6:9], v[174:177], v[214:217], v[6:9]
	v_mfma_f32_16x16x32_bf16 v[2:5], v[182:185], v[214:217], v[2:5]
	s_add_i32 s39, s39, 2
	s_add_u32 s12, s12, 0x100
	s_addc_u32 s13, s13, 0
	s_add_u32 s7, s7, 0x100
	s_addc_u32 s19, s19, 0
	s_cmp_gt_u32 s39, 13
	s_barrier
	s_cbranch_scc0 .LBB0_1254
	s_and_b64 vcc, exec, s[34:35]
	s_cbranch_vccz .LBB0_1257
	s_barrier

.LBB0_1449:
	ds_read_b128 v[154:157], v151
	ds_read_b128 v[158:161], v151 offset:1024
	ds_read_b128 v[162:165], v151 offset:2048
	ds_read_b128 v[166:169], v151 offset:3072
	ds_read_b128 v[170:173], v152
	ds_read_b128 v[174:177], v152 offset:1024
	ds_read_b128 v[178:181], v152 offset:2048
	ds_read_b128 v[182:185], v152 offset:3072
	s_add_u32 s34, s30, 0xfffc0080
	s_addc_u32 s35, s31, -1
	s_cmp_eq_u32 s45, 12
	s_cselect_b32 s37, s27, s35
	s_cselect_b32 s36, s26, s34
	s_cselect_b32 s35, s29, s19
	s_cselect_b32 s34, s28, s17
	v_lshl_add_u64 v[220:221], s[30:31], 0, v[138:139]
	s_add_i32 m0, s25, 0xc000
	ds_read_b128 v[186:189], v153
	ds_read_b128 v[190:193], v153 offset:1024
	ds_read_b128 v[194:197], v153 offset:2048
	ds_read_b128 v[198:201], v153 offset:3072
	ds_read_b128 v[202:205], v153 offset:4096
	ds_read_b128 v[208:211], v153 offset:5120
	ds_read_b128 v[212:215], v153 offset:6144
	ds_read_b128 v[216:219], v153 offset:7168
	global_load_lds_dwordx4 v[220:221], off
	v_lshl_add_u64 v[220:221], s[30:31], 0, v[140:141]
	s_add_i32 m0, s25, 0xe000
	s_nop 0
	global_load_lds_dwordx4 v[220:221], off
	s_waitcnt vmcnt(8)
	s_waitcnt lgkmcnt(0)
	s_barrier
	s_waitcnt lgkmcnt(0)
	v_mfma_f32_16x16x32_bf16 v[126:129], v[154:157], v[186:189], v[126:129]
	v_mfma_f32_16x16x32_bf16 v[122:125], v[162:165], v[186:189], v[122:125]
	v_mfma_f32_16x16x32_bf16 v[110:113], v[154:157], v[194:197], v[110:113]
	v_mfma_f32_16x16x32_bf16 v[106:109], v[162:165], v[194:197], v[106:109]
	v_mfma_f32_16x16x32_bf16 v[94:97], v[154:157], v[202:205], v[94:97]
	v_mfma_f32_16x16x32_bf16 v[90:93], v[162:165], v[202:205], v[90:93]
	v_mfma_f32_16x16x32_bf16 v[78:81], v[154:157], v[212:215], v[78:81]
	v_mfma_f32_16x16x32_bf16 v[74:77], v[162:165], v[212:215], v[74:77]
	v_mfma_f32_16x16x32_bf16 v[126:129], v[158:161], v[190:193], v[126:129]
	v_mfma_f32_16x16x32_bf16 v[122:125], v[166:169], v[190:193], v[122:125]
	v_mfma_f32_16x16x32_bf16 v[110:113], v[158:161], v[198:201], v[110:113]
	v_mfma_f32_16x16x32_bf16 v[106:109], v[166:169], v[198:201], v[106:109]
	v_mfma_f32_16x16x32_bf16 v[94:97], v[158:161], v[208:211], v[94:97]
	v_mfma_f32_16x16x32_bf16 v[90:93], v[166:169], v[208:211], v[90:93]
	v_mfma_f32_16x16x32_bf16 v[78:81], v[158:161], v[216:219], v[78:81]
	v_mfma_f32_16x16x32_bf16 v[74:77], v[166:169], v[216:219], v[74:77]
	v_mfma_f32_16x16x32_bf16 v[118:121], v[170:173], v[186:189], v[118:121]
	v_mfma_f32_16x16x32_bf16 v[114:117], v[178:181], v[186:189], v[114:117]
	v_mfma_f32_16x16x32_bf16 v[102:105], v[170:173], v[194:197], v[102:105]
	v_mfma_f32_16x16x32_bf16 v[98:101], v[178:181], v[194:197], v[98:101]
	v_mfma_f32_16x16x32_bf16 v[86:89], v[170:173], v[202:205], v[86:89]
	v_mfma_f32_16x16x32_bf16 v[82:85], v[178:181], v[202:205], v[82:85]
	v_mfma_f32_16x16x32_bf16 v[70:73], v[170:173], v[212:215], v[70:73]
	v_mfma_f32_16x16x32_bf16 v[66:69], v[178:181], v[212:215], v[66:69]
	v_mfma_f32_16x16x32_bf16 v[118:121], v[174:177], v[190:193], v[118:121]
	v_mfma_f32_16x16x32_bf16 v[114:117], v[182:185], v[190:193], v[114:117]
	v_mfma_f32_16x16x32_bf16 v[102:105], v[174:177], v[198:201], v[102:105]
	v_mfma_f32_16x16x32_bf16 v[98:101], v[182:185], v[198:201], v[98:101]
	v_mfma_f32_16x16x32_bf16 v[86:89], v[174:177], v[208:211], v[86:89]
	v_mfma_f32_16x16x32_bf16 v[82:85], v[182:185], v[208:211], v[82:85]
	v_mfma_f32_16x16x32_bf16 v[70:73], v[174:177], v[216:219], v[70:73]
	v_mfma_f32_16x16x32_bf16 v[66:69], v[182:185], v[216:219], v[66:69]
	s_barrier
	s_add_i32 s57, s54, s41
	v_lshl_add_u64 v[220:221], s[34:35], 0, v[132:133]
	s_mov_b32 m0, s57
	ds_read_b128 v[186:189], v153 offset:16384
	ds_read_b128 v[190:193], v153 offset:17408
	ds_read_b128 v[194:197], v153 offset:18432
	ds_read_b128 v[198:201], v153 offset:19456
	ds_read_b128 v[202:205], v153 offset:20480
	ds_read_b128 v[208:211], v153 offset:21504
	ds_read_b128 v[212:215], v153 offset:22528
	ds_read_b128 v[216:219], v153 offset:23552
	global_load_lds_dwordx4 v[220:221], off
	s_add_i32 m0, s57, 0x2000
	s_add_u32 s58, s34, 0x580000
	v_lshl_add_u64 v[222:223], s[34:35], 0, v[136:137]
	s_addc_u32 s59, s35, 0
	s_add_i32 s57, s55, s41
	global_load_lds_dwordx4 v[222:223], off
	v_lshl_add_u64 v[224:225], s[58:59], 0, v[132:133]
	s_mov_b32 m0, s57
	v_lshl_add_u64 v[226:227], s[36:37], 0, v[134:135]
	global_load_lds_dwordx4 v[224:225], off
	v_lshl_add_u64 v[224:225], s[58:59], 0, v[136:137]
	s_add_i32 m0, s57, 0x2000
	s_nop 0
	global_load_lds_dwordx4 v[224:225], off
	v_lshl_add_u64 v[224:225], s[36:37], 0, v[130:131]
	s_mov_b32 m0, s25
	s_nop 0
	global_load_lds_dwordx4 v[224:225], off
	s_mov_b32 m0, s46
	s_nop 0
	global_load_lds_dwordx4 v[226:227], off
	s_waitcnt vmcnt(8)
	s_waitcnt lgkmcnt(0)
	s_barrier
	s_waitcnt lgkmcnt(0)
	v_mfma_f32_16x16x32_bf16 v[62:65], v[154:157], v[186:189], v[62:65]
	v_mfma_f32_16x16x32_bf16 v[58:61], v[162:165], v[186:189], v[58:61]
	v_mfma_f32_16x16x32_bf16 v[46:49], v[154:157], v[194:197], v[46:49]
	v_mfma_f32_16x16x32_bf16 v[42:45], v[162:165], v[194:197], v[42:45]
	v_mfma_f32_16x16x32_bf16 v[30:33], v[154:157], v[202:205], v[30:33]
	v_mfma_f32_16x16x32_bf16 v[26:29], v[162:165], v[202:205], v[26:29]
	v_mfma_f32_16x16x32_bf16 v[14:17], v[154:157], v[212:215], v[14:17]
	v_mfma_f32_16x16x32_bf16 v[10:13], v[162:165], v[212:215], v[10:13]
	v_mfma_f32_16x16x32_bf16 v[62:65], v[158:161], v[190:193], v[62:65]
	v_mfma_f32_16x16x32_bf16 v[58:61], v[166:169], v[190:193], v[58:61]
	v_mfma_f32_16x16x32_bf16 v[46:49], v[158:161], v[198:201], v[46:49]
	v_mfma_f32_16x16x32_bf16 v[42:45], v[166:169], v[198:201], v[42:45]
	v_mfma_f32_16x16x32_bf16 v[30:33], v[158:161], v[208:211], v[30:33]
	v_mfma_f32_16x16x32_bf16 v[26:29], v[166:169], v[208:211], v[26:29]
	v_mfma_f32_16x16x32_bf16 v[14:17], v[158:161], v[216:219], v[14:17]
	v_mfma_f32_16x16x32_bf16 v[10:13], v[166:169], v[216:219], v[10:13]
	v_mfma_f32_16x16x32_bf16 v[54:57], v[170:173], v[186:189], v[54:57]
	v_mfma_f32_16x16x32_bf16 v[50:53], v[178:181], v[186:189], v[50:53]
	v_mfma_f32_16x16x32_bf16 v[38:41], v[170:173], v[194:197], v[38:41]
	v_mfma_f32_16x16x32_bf16 v[34:37], v[178:181], v[194:197], v[34:37]
	v_mfma_f32_16x16x32_bf16 v[22:25], v[170:173], v[202:205], v[22:25]
	v_mfma_f32_16x16x32_bf16 v[18:21], v[178:181], v[202:205], v[18:21]
	v_mfma_f32_16x16x32_bf16 v[6:9], v[170:173], v[212:215], v[6:9]
	v_mfma_f32_16x16x32_bf16 v[2:5], v[178:181], v[212:215], v[2:5]
	v_mfma_f32_16x16x32_bf16 v[54:57], v[174:177], v[190:193], v[54:57]
	v_mfma_f32_16x16x32_bf16 v[50:53], v[182:185], v[190:193], v[50:53]
	v_mfma_f32_16x16x32_bf16 v[38:41], v[174:177], v[198:201], v[38:41]
	v_mfma_f32_16x16x32_bf16 v[34:37], v[182:185], v[198:201], v[34:37]
	v_mfma_f32_16x16x32_bf16 v[22:25], v[174:177], v[208:211], v[22:25]
	v_mfma_f32_16x16x32_bf16 v[18:21], v[182:185], v[208:211], v[18:21]
	v_mfma_f32_16x16x32_bf16 v[6:9], v[174:177], v[216:219], v[6:9]
	v_mfma_f32_16x16x32_bf16 v[2:5], v[182:185], v[216:219], v[2:5]
	s_barrier
	s_add_i32 s57, 0, 0x18000
	s_add_i32 s58, 0, 0x1c000
	v_add_u32_e32 v166, s57, v149
	v_add_u32_e32 v182, s58, v149
	ds_read_b128 v[154:157], v166
	ds_read_b128 v[158:161], v166 offset:1024
	ds_read_b128 v[162:165], v166 offset:2048
	ds_read_b128 v[166:169], v166 offset:3072
	ds_read_b128 v[170:173], v182
	ds_read_b128 v[174:177], v182 offset:1024
	ds_read_b128 v[178:181], v182 offset:2048
	ds_read_b128 v[182:185], v182 offset:3072
	s_add_u32 s36, s36, 0x40000
	s_addc_u32 s37, s37, 0
	s_mov_b32 m0, s47
	v_lshl_add_u64 v[228:229], s[36:37], 0, v[130:131]
	ds_read_b128 v[186:189], v153 offset:32768
	ds_read_b128 v[190:193], v153 offset:33792
	ds_read_b128 v[194:197], v153 offset:34816
	ds_read_b128 v[198:201], v153 offset:35840
	ds_read_b128 v[202:205], v153 offset:36864
	ds_read_b128 v[208:211], v153 offset:37888
	ds_read_b128 v[212:215], v153 offset:38912
	ds_read_b128 v[216:219], v153 offset:39936
	global_load_lds_dwordx4 v[228:229], off
	v_lshl_add_u64 v[228:229], s[36:37], 0, v[134:135]
	s_mov_b32 m0, s48
	s_nop 0
	global_load_lds_dwordx4 v[228:229], off
	s_waitcnt vmcnt(8)
	s_waitcnt lgkmcnt(0)
	s_barrier
	s_waitcnt lgkmcnt(0)
	v_mfma_f32_16x16x32_bf16 v[126:129], v[154:157], v[186:189], v[126:129]
	v_mfma_f32_16x16x32_bf16 v[122:125], v[162:165], v[186:189], v[122:125]
	v_mfma_f32_16x16x32_bf16 v[110:113], v[154:157], v[194:197], v[110:113]
	v_mfma_f32_16x16x32_bf16 v[106:109], v[162:165], v[194:197], v[106:109]
	v_mfma_f32_16x16x32_bf16 v[94:97], v[154:157], v[202:205], v[94:97]
	v_mfma_f32_16x16x32_bf16 v[90:93], v[162:165], v[202:205], v[90:93]
	v_mfma_f32_16x16x32_bf16 v[78:81], v[154:157], v[212:215], v[78:81]
	v_mfma_f32_16x16x32_bf16 v[74:77], v[162:165], v[212:215], v[74:77]
	v_mfma_f32_16x16x32_bf16 v[126:129], v[158:161], v[190:193], v[126:129]
	v_mfma_f32_16x16x32_bf16 v[122:125], v[166:169], v[190:193], v[122:125]
	v_mfma_f32_16x16x32_bf16 v[110:113], v[158:161], v[198:201], v[110:113]
	v_mfma_f32_16x16x32_bf16 v[106:109], v[166:169], v[198:201], v[106:109]
	v_mfma_f32_16x16x32_bf16 v[94:97], v[158:161], v[208:211], v[94:97]
	v_mfma_f32_16x16x32_bf16 v[90:93], v[166:169], v[208:211], v[90:93]
	v_mfma_f32_16x16x32_bf16 v[78:81], v[158:161], v[216:219], v[78:81]
	v_mfma_f32_16x16x32_bf16 v[74:77], v[166:169], v[216:219], v[74:77]
	v_mfma_f32_16x16x32_bf16 v[118:121], v[170:173], v[186:189], v[118:121]
	v_mfma_f32_16x16x32_bf16 v[114:117], v[178:181], v[186:189], v[114:117]
	v_mfma_f32_16x16x32_bf16 v[102:105], v[170:173], v[194:197], v[102:105]
	v_mfma_f32_16x16x32_bf16 v[98:101], v[178:181], v[194:197], v[98:101]
	v_mfma_f32_16x16x32_bf16 v[86:89], v[170:173], v[202:205], v[86:89]
	v_mfma_f32_16x16x32_bf16 v[82:85], v[178:181], v[202:205], v[82:85]
	v_mfma_f32_16x16x32_bf16 v[70:73], v[170:173], v[212:215], v[70:73]
	v_mfma_f32_16x16x32_bf16 v[66:69], v[178:181], v[212:215], v[66:69]
	v_mfma_f32_16x16x32_bf16 v[118:121], v[174:177], v[190:193], v[118:121]
	v_mfma_f32_16x16x32_bf16 v[114:117], v[182:185], v[190:193], v[114:117]
	v_mfma_f32_16x16x32_bf16 v[102:105], v[174:177], v[198:201], v[102:105]
	v_mfma_f32_16x16x32_bf16 v[98:101], v[182:185], v[198:201], v[98:101]
	v_mfma_f32_16x16x32_bf16 v[86:89], v[174:177], v[208:211], v[86:89]
	v_mfma_f32_16x16x32_bf16 v[82:85], v[182:185], v[208:211], v[82:85]
	v_mfma_f32_16x16x32_bf16 v[70:73], v[174:177], v[216:219], v[70:73]
	v_mfma_f32_16x16x32_bf16 v[66:69], v[182:185], v[216:219], v[66:69]
	s_barrier
	s_add_i32 s36, s57, s41
	v_lshl_add_u64 v[220:221], v[220:221], 0, s[12:13]
	s_mov_b32 m0, s36
	ds_read_b128 v[186:189], v153 offset:49152
	ds_read_b128 v[190:193], v153 offset:50176
	ds_read_b128 v[194:197], v153 offset:51200
	ds_read_b128 v[198:201], v153 offset:52224
	ds_read_b128 v[202:205], v153 offset:53248
	ds_read_b128 v[208:211], v153 offset:54272
	ds_read_b128 v[212:215], v153 offset:55296
	ds_read_b128 v[216:219], v153 offset:56320
	global_load_lds_dwordx4 v[220:221], off
	s_add_i32 m0, s36, 0x2000
	s_add_u32 s34, s34, 0x580080
	v_lshl_add_u64 v[220:221], v[222:223], 0, s[12:13]
	s_addc_u32 s35, s35, 0
	s_add_i32 s36, s58, s41
	global_load_lds_dwordx4 v[220:221], off
	v_lshl_add_u64 v[220:221], s[34:35], 0, v[132:133]
	s_mov_b32 m0, s36
	s_nop 0
	global_load_lds_dwordx4 v[220:221], off
	v_lshl_add_u64 v[220:221], s[34:35], 0, v[136:137]
	s_add_i32 m0, s36, 0x2000
	s_nop 0
	global_load_lds_dwordx4 v[220:221], off
	v_lshl_add_u64 v[220:221], v[224:225], 0, s[12:13]
	s_mov_b32 m0, s51
	s_nop 0
	global_load_lds_dwordx4 v[220:221], off
	v_lshl_add_u64 v[220:221], v[226:227], 0, s[12:13]
	s_mov_b32 m0, s52
	s_nop 0
	global_load_lds_dwordx4 v[220:221], off
	s_waitcnt vmcnt(8)
	s_waitcnt lgkmcnt(0)
	s_barrier
	s_waitcnt lgkmcnt(0)
	v_mfma_f32_16x16x32_bf16 v[62:65], v[154:157], v[186:189], v[62:65]
	v_mfma_f32_16x16x32_bf16 v[58:61], v[162:165], v[186:189], v[58:61]
	v_mfma_f32_16x16x32_bf16 v[46:49], v[154:157], v[194:197], v[46:49]
	v_mfma_f32_16x16x32_bf16 v[42:45], v[162:165], v[194:197], v[42:45]
	v_mfma_f32_16x16x32_bf16 v[30:33], v[154:157], v[202:205], v[30:33]
	v_mfma_f32_16x16x32_bf16 v[26:29], v[162:165], v[202:205], v[26:29]
	v_mfma_f32_16x16x32_bf16 v[14:17], v[154:157], v[212:215], v[14:17]
	v_mfma_f32_16x16x32_bf16 v[10:13], v[162:165], v[212:215], v[10:13]
	v_mfma_f32_16x16x32_bf16 v[62:65], v[158:161], v[190:193], v[62:65]
	v_mfma_f32_16x16x32_bf16 v[58:61], v[166:169], v[190:193], v[58:61]
	v_mfma_f32_16x16x32_bf16 v[46:49], v[158:161], v[198:201], v[46:49]
	v_mfma_f32_16x16x32_bf16 v[42:45], v[166:169], v[198:201], v[42:45]
	v_mfma_f32_16x16x32_bf16 v[30:33], v[158:161], v[208:211], v[30:33]
	v_mfma_f32_16x16x32_bf16 v[26:29], v[166:169], v[208:211], v[26:29]
	v_mfma_f32_16x16x32_bf16 v[14:17], v[158:161], v[216:219], v[14:17]
	v_mfma_f32_16x16x32_bf16 v[10:13], v[166:169], v[216:219], v[10:13]
	v_mfma_f32_16x16x32_bf16 v[54:57], v[170:173], v[186:189], v[54:57]
	v_mfma_f32_16x16x32_bf16 v[50:53], v[178:181], v[186:189], v[50:53]
	v_mfma_f32_16x16x32_bf16 v[38:41], v[170:173], v[194:197], v[38:41]
	v_mfma_f32_16x16x32_bf16 v[34:37], v[178:181], v[194:197], v[34:37]
	v_mfma_f32_16x16x32_bf16 v[22:25], v[170:173], v[202:205], v[22:25]
	v_mfma_f32_16x16x32_bf16 v[18:21], v[178:181], v[202:205], v[18:21]
	v_mfma_f32_16x16x32_bf16 v[6:9], v[170:173], v[212:215], v[6:9]
	v_mfma_f32_16x16x32_bf16 v[2:5], v[178:181], v[212:215], v[2:5]
	v_mfma_f32_16x16x32_bf16 v[54:57], v[174:177], v[190:193], v[54:57]
	v_mfma_f32_16x16x32_bf16 v[50:53], v[182:185], v[190:193], v[50:53]
	v_mfma_f32_16x16x32_bf16 v[38:41], v[174:177], v[198:201], v[38:41]
	v_mfma_f32_16x16x32_bf16 v[34:37], v[182:185], v[198:201], v[34:37]
	v_mfma_f32_16x16x32_bf16 v[22:25], v[174:177], v[208:211], v[22:25]
	v_mfma_f32_16x16x32_bf16 v[18:21], v[182:185], v[208:211], v[18:21]
	v_mfma_f32_16x16x32_bf16 v[6:9], v[174:177], v[216:219], v[6:9]
	v_mfma_f32_16x16x32_bf16 v[2:5], v[182:185], v[216:219], v[2:5]
	s_add_i32 s45, s45, 2
	s_add_u32 s30, s30, 0x100
	s_addc_u32 s31, s31, 0
	s_add_u32 s17, s17, 0x100
	s_addc_u32 s19, s19, 0
	s_cmp_gt_u32 s45, 13
	s_barrier
	s_cbranch_scc0 .LBB0_1449
	s_and_b64 vcc, exec, s[14:15]
	s_cbranch_vccz .LBB0_1452
	s_barrier

.LBB0_1541:
	ds_read_b128 v[130:133], v210
	ds_read_b128 v[134:137], v210 offset:1024
	ds_read_b128 v[138:141], v210 offset:2048
	ds_read_b128 v[142:145], v210 offset:3072
	ds_read_b128 v[146:149], v211
	ds_read_b128 v[150:153], v211 offset:1024
	ds_read_b128 v[154:157], v211 offset:2048
	ds_read_b128 v[158:161], v211 offset:3072
	s_add_u32 s40, s38, 0xfff50080
	s_addc_u32 s41, s39, -1
	s_cmp_eq_u32 s77, 40
	s_cselect_b32 s43, s35, s41
	s_cselect_b32 s42, s34, s40
	s_cselect_b32 s41, s37, s45
	s_cselect_b32 s40, s36, s44
	v_lshl_add_u64 v[218:219], s[38:39], 0, v[178:179]
	s_add_i32 m0, s50, 0xc000
	ds_read_b128 v[162:165], v212
	ds_read_b128 v[166:169], v212 offset:1024
	ds_read_b128 v[186:189], v212 offset:2048
	ds_read_b128 v[190:193], v212 offset:3072
	ds_read_b128 v[194:197], v212 offset:4096
	ds_read_b128 v[198:201], v212 offset:5120
	ds_read_b128 v[202:205], v212 offset:6144
	ds_read_b128 v[214:217], v212 offset:7168
	global_load_lds_dwordx4 v[218:219], off
	v_lshl_add_u64 v[218:219], s[38:39], 0, v[180:181]
	s_add_i32 m0, s50, 0xe000
	s_nop 0
	global_load_lds_dwordx4 v[218:219], off
	s_waitcnt vmcnt(8)
	s_waitcnt lgkmcnt(0)
	s_barrier
	s_waitcnt lgkmcnt(0)
	v_mfma_f32_16x16x32_bf16 v[126:129], v[130:133], v[162:165], v[126:129]
	v_mfma_f32_16x16x32_bf16 v[122:125], v[138:141], v[162:165], v[122:125]
	v_mfma_f32_16x16x32_bf16 v[118:121], v[130:133], v[186:189], v[118:121]
	v_mfma_f32_16x16x32_bf16 v[114:117], v[138:141], v[186:189], v[114:117]
	v_mfma_f32_16x16x32_bf16 v[110:113], v[130:133], v[194:197], v[110:113]
	v_mfma_f32_16x16x32_bf16 v[106:109], v[138:141], v[194:197], v[106:109]
	v_mfma_f32_16x16x32_bf16 v[102:105], v[130:133], v[202:205], v[102:105]
	v_mfma_f32_16x16x32_bf16 v[98:101], v[138:141], v[202:205], v[98:101]
	v_mfma_f32_16x16x32_bf16 v[126:129], v[134:137], v[166:169], v[126:129]
	v_mfma_f32_16x16x32_bf16 v[122:125], v[142:145], v[166:169], v[122:125]
	v_mfma_f32_16x16x32_bf16 v[118:121], v[134:137], v[190:193], v[118:121]
	v_mfma_f32_16x16x32_bf16 v[114:117], v[142:145], v[190:193], v[114:117]
	v_mfma_f32_16x16x32_bf16 v[110:113], v[134:137], v[198:201], v[110:113]
	v_mfma_f32_16x16x32_bf16 v[106:109], v[142:145], v[198:201], v[106:109]
	v_mfma_f32_16x16x32_bf16 v[102:105], v[134:137], v[214:217], v[102:105]
	v_mfma_f32_16x16x32_bf16 v[98:101], v[142:145], v[214:217], v[98:101]
	v_mfma_f32_16x16x32_bf16 v[70:73], v[146:149], v[162:165], v[70:73]
	v_mfma_f32_16x16x32_bf16 v[66:69], v[154:157], v[162:165], v[66:69]
	v_mfma_f32_16x16x32_bf16 v[62:65], v[146:149], v[186:189], v[62:65]
	v_mfma_f32_16x16x32_bf16 v[54:57], v[154:157], v[186:189], v[54:57]
	v_mfma_f32_16x16x32_bf16 v[46:49], v[146:149], v[194:197], v[46:49]
	v_mfma_f32_16x16x32_bf16 v[42:45], v[154:157], v[194:197], v[42:45]
	v_mfma_f32_16x16x32_bf16 v[38:41], v[146:149], v[202:205], v[38:41]
	v_mfma_f32_16x16x32_bf16 v[34:37], v[154:157], v[202:205], v[34:37]
	v_mfma_f32_16x16x32_bf16 v[70:73], v[150:153], v[166:169], v[70:73]
	v_mfma_f32_16x16x32_bf16 v[66:69], v[158:161], v[166:169], v[66:69]
	v_mfma_f32_16x16x32_bf16 v[62:65], v[150:153], v[190:193], v[62:65]
	v_mfma_f32_16x16x32_bf16 v[54:57], v[158:161], v[190:193], v[54:57]
	v_mfma_f32_16x16x32_bf16 v[46:49], v[150:153], v[198:201], v[46:49]
	v_mfma_f32_16x16x32_bf16 v[42:45], v[158:161], v[198:201], v[42:45]
	v_mfma_f32_16x16x32_bf16 v[38:41], v[150:153], v[214:217], v[38:41]
	v_mfma_f32_16x16x32_bf16 v[34:37], v[158:161], v[214:217], v[34:37]
	s_barrier
	s_add_i32 s78, s61, s48
	v_lshl_add_u64 v[218:219], s[40:41], 0, v[172:173]
	s_mov_b32 m0, s78
	ds_read_b128 v[162:165], v212 offset:16384
	ds_read_b128 v[166:169], v212 offset:17408
	ds_read_b128 v[186:189], v212 offset:18432
	ds_read_b128 v[190:193], v212 offset:19456
	ds_read_b128 v[194:197], v212 offset:20480
	ds_read_b128 v[198:201], v212 offset:21504
	ds_read_b128 v[202:205], v212 offset:22528
	ds_read_b128 v[214:217], v212 offset:23552
	global_load_lds_dwordx4 v[218:219], off
	s_add_i32 m0, s78, 0x2000
	s_add_u32 s78, s40, 0xb0000
	v_lshl_add_u64 v[220:221], s[40:41], 0, v[176:177]
	s_addc_u32 s79, s41, 0
	s_add_i32 s80, s62, s48
	global_load_lds_dwordx4 v[220:221], off
	v_lshl_add_u64 v[222:223], s[78:79], 0, v[172:173]
	s_mov_b32 m0, s80
	v_lshl_add_u64 v[224:225], s[42:43], 0, v[174:175]
	global_load_lds_dwordx4 v[222:223], off
	v_lshl_add_u64 v[222:223], s[78:79], 0, v[176:177]
	s_add_i32 m0, s80, 0x2000
	s_nop 0
	global_load_lds_dwordx4 v[222:223], off
	v_lshl_add_u64 v[222:223], s[42:43], 0, v[170:171]
	s_mov_b32 m0, s50
	s_nop 0
	global_load_lds_dwordx4 v[222:223], off
	s_mov_b32 m0, s51
	s_nop 0
	global_load_lds_dwordx4 v[224:225], off
	s_waitcnt vmcnt(8)
	s_waitcnt lgkmcnt(0)
	s_barrier
	s_waitcnt lgkmcnt(0)
	v_mfma_f32_16x16x32_bf16 v[94:97], v[130:133], v[162:165], v[94:97]
	v_mfma_f32_16x16x32_bf16 v[90:93], v[138:141], v[162:165], v[90:93]
	v_mfma_f32_16x16x32_bf16 v[86:89], v[130:133], v[186:189], v[86:89]
	v_mfma_f32_16x16x32_bf16 v[82:85], v[138:141], v[186:189], v[82:85]
	v_mfma_f32_16x16x32_bf16 v[78:81], v[130:133], v[194:197], v[78:81]
	v_mfma_f32_16x16x32_bf16 v[74:77], v[138:141], v[194:197], v[74:77]
	v_mfma_f32_16x16x32_bf16 v[58:61], v[130:133], v[202:205], v[58:61]
	v_mfma_f32_16x16x32_bf16 v[50:53], v[138:141], v[202:205], v[50:53]
	v_mfma_f32_16x16x32_bf16 v[94:97], v[134:137], v[166:169], v[94:97]
	v_mfma_f32_16x16x32_bf16 v[90:93], v[142:145], v[166:169], v[90:93]
	v_mfma_f32_16x16x32_bf16 v[86:89], v[134:137], v[190:193], v[86:89]
	v_mfma_f32_16x16x32_bf16 v[82:85], v[142:145], v[190:193], v[82:85]
	v_mfma_f32_16x16x32_bf16 v[78:81], v[134:137], v[198:201], v[78:81]
	v_mfma_f32_16x16x32_bf16 v[74:77], v[142:145], v[198:201], v[74:77]
	v_mfma_f32_16x16x32_bf16 v[58:61], v[134:137], v[214:217], v[58:61]
	v_mfma_f32_16x16x32_bf16 v[50:53], v[142:145], v[214:217], v[50:53]
	v_mfma_f32_16x16x32_bf16 v[30:33], v[146:149], v[162:165], v[30:33]
	v_mfma_f32_16x16x32_bf16 v[26:29], v[154:157], v[162:165], v[26:29]
	v_mfma_f32_16x16x32_bf16 v[22:25], v[146:149], v[186:189], v[22:25]
	v_mfma_f32_16x16x32_bf16 v[18:21], v[154:157], v[186:189], v[18:21]
	v_mfma_f32_16x16x32_bf16 v[14:17], v[146:149], v[194:197], v[14:17]
	v_mfma_f32_16x16x32_bf16 v[10:13], v[154:157], v[194:197], v[10:13]
	v_mfma_f32_16x16x32_bf16 v[6:9], v[146:149], v[202:205], v[6:9]
	v_mfma_f32_16x16x32_bf16 v[2:5], v[154:157], v[202:205], v[2:5]
	v_mfma_f32_16x16x32_bf16 v[30:33], v[150:153], v[166:169], v[30:33]
	v_mfma_f32_16x16x32_bf16 v[26:29], v[158:161], v[166:169], v[26:29]
	v_mfma_f32_16x16x32_bf16 v[22:25], v[150:153], v[190:193], v[22:25]
	v_mfma_f32_16x16x32_bf16 v[18:21], v[158:161], v[190:193], v[18:21]
	v_mfma_f32_16x16x32_bf16 v[14:17], v[150:153], v[198:201], v[14:17]
	v_mfma_f32_16x16x32_bf16 v[10:13], v[158:161], v[198:201], v[10:13]
	v_mfma_f32_16x16x32_bf16 v[6:9], v[150:153], v[214:217], v[6:9]
	v_mfma_f32_16x16x32_bf16 v[2:5], v[158:161], v[214:217], v[2:5]
	s_barrier
	s_add_i32 s78, 0, 0x18000
	s_add_i32 s79, 0, 0x1c000
	v_add_u32_e32 v142, s78, v208
	v_add_u32_e32 v158, s79, v208
	ds_read_b128 v[130:133], v142
	ds_read_b128 v[134:137], v142 offset:1024
	ds_read_b128 v[138:141], v142 offset:2048
	ds_read_b128 v[142:145], v142 offset:3072
	ds_read_b128 v[146:149], v158
	ds_read_b128 v[150:153], v158 offset:1024
	ds_read_b128 v[154:157], v158 offset:2048
	ds_read_b128 v[158:161], v158 offset:3072
	s_add_u32 s42, s42, 0xb0000
	s_addc_u32 s43, s43, 0
	s_mov_b32 m0, s52
	v_lshl_add_u64 v[226:227], s[42:43], 0, v[170:171]
	ds_read_b128 v[162:165], v212 offset:32768
	ds_read_b128 v[166:169], v212 offset:33792
	ds_read_b128 v[186:189], v212 offset:34816
	ds_read_b128 v[190:193], v212 offset:35840
	ds_read_b128 v[194:197], v212 offset:36864
	ds_read_b128 v[198:201], v212 offset:37888
	ds_read_b128 v[202:205], v212 offset:38912
	ds_read_b128 v[214:217], v212 offset:39936
	global_load_lds_dwordx4 v[226:227], off
	v_lshl_add_u64 v[226:227], s[42:43], 0, v[174:175]
	s_mov_b32 m0, s53
	s_nop 0
	global_load_lds_dwordx4 v[226:227], off
	s_waitcnt vmcnt(8)
	s_waitcnt lgkmcnt(0)
	s_barrier
	s_waitcnt lgkmcnt(0)
	v_mfma_f32_16x16x32_bf16 v[126:129], v[130:133], v[162:165], v[126:129]
	v_mfma_f32_16x16x32_bf16 v[122:125], v[138:141], v[162:165], v[122:125]
	v_mfma_f32_16x16x32_bf16 v[118:121], v[130:133], v[186:189], v[118:121]
	v_mfma_f32_16x16x32_bf16 v[114:117], v[138:141], v[186:189], v[114:117]
	v_mfma_f32_16x16x32_bf16 v[110:113], v[130:133], v[194:197], v[110:113]
	v_mfma_f32_16x16x32_bf16 v[106:109], v[138:141], v[194:197], v[106:109]
	v_mfma_f32_16x16x32_bf16 v[102:105], v[130:133], v[202:205], v[102:105]
	v_mfma_f32_16x16x32_bf16 v[98:101], v[138:141], v[202:205], v[98:101]
	v_mfma_f32_16x16x32_bf16 v[126:129], v[134:137], v[166:169], v[126:129]
	v_mfma_f32_16x16x32_bf16 v[122:125], v[142:145], v[166:169], v[122:125]
	v_mfma_f32_16x16x32_bf16 v[118:121], v[134:137], v[190:193], v[118:121]
	v_mfma_f32_16x16x32_bf16 v[114:117], v[142:145], v[190:193], v[114:117]
	v_mfma_f32_16x16x32_bf16 v[110:113], v[134:137], v[198:201], v[110:113]
	v_mfma_f32_16x16x32_bf16 v[106:109], v[142:145], v[198:201], v[106:109]
	v_mfma_f32_16x16x32_bf16 v[102:105], v[134:137], v[214:217], v[102:105]
	v_mfma_f32_16x16x32_bf16 v[98:101], v[142:145], v[214:217], v[98:101]
	v_mfma_f32_16x16x32_bf16 v[70:73], v[146:149], v[162:165], v[70:73]
	v_mfma_f32_16x16x32_bf16 v[66:69], v[154:157], v[162:165], v[66:69]
	v_mfma_f32_16x16x32_bf16 v[62:65], v[146:149], v[186:189], v[62:65]
	v_mfma_f32_16x16x32_bf16 v[54:57], v[154:157], v[186:189], v[54:57]
	v_mfma_f32_16x16x32_bf16 v[46:49], v[146:149], v[194:197], v[46:49]
	v_mfma_f32_16x16x32_bf16 v[42:45], v[154:157], v[194:197], v[42:45]
	v_mfma_f32_16x16x32_bf16 v[38:41], v[146:149], v[202:205], v[38:41]
	v_mfma_f32_16x16x32_bf16 v[34:37], v[154:157], v[202:205], v[34:37]
	v_mfma_f32_16x16x32_bf16 v[70:73], v[150:153], v[166:169], v[70:73]
	v_mfma_f32_16x16x32_bf16 v[66:69], v[158:161], v[166:169], v[66:69]
	v_mfma_f32_16x16x32_bf16 v[62:65], v[150:153], v[190:193], v[62:65]
	v_mfma_f32_16x16x32_bf16 v[54:57], v[158:161], v[190:193], v[54:57]
	v_mfma_f32_16x16x32_bf16 v[46:49], v[150:153], v[198:201], v[46:49]
	v_mfma_f32_16x16x32_bf16 v[42:45], v[158:161], v[198:201], v[42:45]
	v_mfma_f32_16x16x32_bf16 v[38:41], v[150:153], v[214:217], v[38:41]
	v_mfma_f32_16x16x32_bf16 v[34:37], v[158:161], v[214:217], v[34:37]
	s_barrier
	s_add_i32 s42, s78, s48
	v_lshl_add_u64 v[218:219], v[218:219], 0, s[14:15]
	s_mov_b32 m0, s42
	ds_read_b128 v[162:165], v212 offset:49152
	ds_read_b128 v[166:169], v212 offset:50176
	ds_read_b128 v[186:189], v212 offset:51200
	ds_read_b128 v[190:193], v212 offset:52224
	ds_read_b128 v[194:197], v212 offset:53248
	ds_read_b128 v[198:201], v212 offset:54272
	ds_read_b128 v[202:205], v212 offset:55296
	ds_read_b128 v[214:217], v212 offset:56320
	global_load_lds_dwordx4 v[218:219], off
	s_add_i32 m0, s42, 0x2000
	s_add_u32 s40, s40, 0xb0080
	v_lshl_add_u64 v[218:219], v[220:221], 0, s[14:15]
	s_addc_u32 s41, s41, 0
	s_add_i32 s42, s79, s48
	global_load_lds_dwordx4 v[218:219], off
	v_lshl_add_u64 v[218:219], s[40:41], 0, v[172:173]
	s_mov_b32 m0, s42
	s_nop 0
	global_load_lds_dwordx4 v[218:219], off
	v_lshl_add_u64 v[218:219], s[40:41], 0, v[176:177]
	s_add_i32 m0, s42, 0x2000
	s_nop 0
	global_load_lds_dwordx4 v[218:219], off
	v_lshl_add_u64 v[218:219], v[222:223], 0, s[14:15]
	s_mov_b32 m0, s58
	s_nop 0
	global_load_lds_dwordx4 v[218:219], off
	v_lshl_add_u64 v[218:219], v[224:225], 0, s[14:15]
	s_mov_b32 m0, s59
	s_nop 0
	global_load_lds_dwordx4 v[218:219], off
	s_waitcnt vmcnt(8)
	s_waitcnt lgkmcnt(0)
	s_barrier
	s_waitcnt lgkmcnt(0)
	v_mfma_f32_16x16x32_bf16 v[94:97], v[130:133], v[162:165], v[94:97]
	v_mfma_f32_16x16x32_bf16 v[90:93], v[138:141], v[162:165], v[90:93]
	v_mfma_f32_16x16x32_bf16 v[86:89], v[130:133], v[186:189], v[86:89]
	v_mfma_f32_16x16x32_bf16 v[82:85], v[138:141], v[186:189], v[82:85]
	v_mfma_f32_16x16x32_bf16 v[78:81], v[130:133], v[194:197], v[78:81]
	v_mfma_f32_16x16x32_bf16 v[74:77], v[138:141], v[194:197], v[74:77]
	v_mfma_f32_16x16x32_bf16 v[58:61], v[130:133], v[202:205], v[58:61]
	v_mfma_f32_16x16x32_bf16 v[50:53], v[138:141], v[202:205], v[50:53]
	v_mfma_f32_16x16x32_bf16 v[94:97], v[134:137], v[166:169], v[94:97]
	v_mfma_f32_16x16x32_bf16 v[90:93], v[142:145], v[166:169], v[90:93]
	v_mfma_f32_16x16x32_bf16 v[86:89], v[134:137], v[190:193], v[86:89]
	v_mfma_f32_16x16x32_bf16 v[82:85], v[142:145], v[190:193], v[82:85]
	v_mfma_f32_16x16x32_bf16 v[78:81], v[134:137], v[198:201], v[78:81]
	v_mfma_f32_16x16x32_bf16 v[74:77], v[142:145], v[198:201], v[74:77]
	v_mfma_f32_16x16x32_bf16 v[58:61], v[134:137], v[214:217], v[58:61]
	v_mfma_f32_16x16x32_bf16 v[50:53], v[142:145], v[214:217], v[50:53]
	v_mfma_f32_16x16x32_bf16 v[30:33], v[146:149], v[162:165], v[30:33]
	v_mfma_f32_16x16x32_bf16 v[26:29], v[154:157], v[162:165], v[26:29]
	v_mfma_f32_16x16x32_bf16 v[22:25], v[146:149], v[186:189], v[22:25]
	v_mfma_f32_16x16x32_bf16 v[18:21], v[154:157], v[186:189], v[18:21]
	v_mfma_f32_16x16x32_bf16 v[14:17], v[146:149], v[194:197], v[14:17]
	v_mfma_f32_16x16x32_bf16 v[10:13], v[154:157], v[194:197], v[10:13]
	v_mfma_f32_16x16x32_bf16 v[6:9], v[146:149], v[202:205], v[6:9]
	v_mfma_f32_16x16x32_bf16 v[2:5], v[154:157], v[202:205], v[2:5]
	v_mfma_f32_16x16x32_bf16 v[30:33], v[150:153], v[166:169], v[30:33]
	v_mfma_f32_16x16x32_bf16 v[26:29], v[158:161], v[166:169], v[26:29]
	v_mfma_f32_16x16x32_bf16 v[22:25], v[150:153], v[190:193], v[22:25]
	v_mfma_f32_16x16x32_bf16 v[18:21], v[158:161], v[190:193], v[18:21]
	v_mfma_f32_16x16x32_bf16 v[14:17], v[150:153], v[198:201], v[14:17]
	v_mfma_f32_16x16x32_bf16 v[10:13], v[158:161], v[198:201], v[10:13]
	v_mfma_f32_16x16x32_bf16 v[6:9], v[150:153], v[214:217], v[6:9]
	v_mfma_f32_16x16x32_bf16 v[2:5], v[158:161], v[214:217], v[2:5]
	s_add_i32 s77, s77, 2
	s_add_u32 s38, s38, 0x100
	s_addc_u32 s39, s39, 0
	s_add_u32 s44, s44, 0x100
	s_addc_u32 s45, s45, 0
	s_cmp_gt_u32 s77, 41
	s_barrier
	s_cbranch_scc0 .LBB0_1541
	s_and_b64 vcc, exec, s[16:17]
	s_cbranch_vccz .LBB0_1544
	s_barrier
